# weight-prep transpose jobs: the 16 serialized flat_load->wait->ds_write steps per job rewritten to issue loads back-to-back into fresh VGPRs with a counted vmcnt ladder
# baseline (speedup 1.0000x reference)
; DI void transpose_job(const int tid_, const float* __restrict__ src, const float* __restrict__ scale, u16* __restrict__ dst, u16* __restrict__ dst2,
;                       int K, int N, int kt, int nt, char* s0, char* s1, char* s2) {
;   float* tile = (float*)s0;
;   const int tid = tid_;
;   __syncthreads();
; #pragma unroll
;   for (int i = 0; i < 16; ++i) {
;     int kl = (tid >> 6) + 4 * i, nl = tid & 63;
;     int k = kt * 64 + kl, n = nt * 64 + nl;
;     tile[kl * 65 + nl] = (n < N) ? src[(size_t)k * N + n] : 0.f;
;   }
;   __syncthreads();
; DI void wprep_job(const int tid_, const Params& p, int l, int j, char* s0, char* s1, char* s2) {
;     ...
;     int q = j - 1784;
;     transpose_job(tid_, p.in[I_WOUT] + (size_t)l * 1024 * 1024, nullptr, (u16*)(p.ws + WS_WOUT) + (size_t)l * 1024 * 1024, nullptr, 1024, 1024, q / 16, q % 16, s0, s1, s2);
;     ...
;       while (true) {
;         __syncthreads();
;         if (tid_ == 0) *sjob = (int)atomicAdd(wq, 1u);
;         __syncthreads();
;         const int j = *sjob;
;         if (j >= 2040) break;
;         wprep_job(opaque_tid(wv), p, l + 1, j, s0, s1, s2);
.LBB0_614:
	s_or_b64 exec, exec, s[2:3]
	s_waitcnt lgkmcnt(0)
	s_barrier
	ds_read_b32 v0, v170
	s_movk_i32 s2, 0x7f7
	s_waitcnt lgkmcnt(0)
	v_cmp_lt_i32_e32 vcc, s2, v0
	v_readfirstlane_b32 s8, v0
	s_mov_b64 s[2:3], -1
	s_cbranch_vccnz .LBB0_611
	v_mbcnt_lo_u32_b32 v34, -1, 0
	v_mbcnt_hi_u32_b32 v34, -1, v34
	s_cmpk_gt_i32 s8, 0x55f
	v_or_b32_e32 v35, s55, v34
	s_cbranch_scc0 .LBB0_705
	s_cmpk_gt_u32 s8, 0x567
	s_cbranch_scc0 .LBB0_702
	s_cmpk_gt_u32 s8, 0x56f
	s_cbranch_scc0 .LBB0_699
	s_cmpk_gt_u32 s8, 0x5b7
	s_cbranch_scc0 .LBB0_664
	s_cmpk_gt_u32 s8, 0x5f7
	s_cbranch_scc0 .LBB0_629
	s_cmpk_gt_u32 s8, 0x677
	s_cbranch_scc0 .LBB0_626
	v_ashrrev_i32_e32 v20, 6, v35
	v_and_b32_e32 v21, 63, v34
	s_movk_i32 s9, 0x104
	v_lshlrev_b32_e32 v2, 2, v21
	v_mul_lo_u32 v0, v20, s9
	v_add_u32_e32 v22, v2, v0
	v_lshlrev_b32_e32 v0, 2, v20
	s_cmpk_gt_u32 s8, 0x6f7
	v_add_u32_e32 v19, 4, v20
	v_add_u32_e32 v18, 8, v20
	v_add_u32_e32 v17, 12, v20
	v_add_u32_e32 v16, 16, v20
	v_add_u32_e32 v15, 20, v20
	v_add_u32_e32 v14, 24, v20
	v_add_u32_e32 v13, 28, v20
	v_add_u32_e32 v12, 32, v20
	v_add_u32_e32 v11, 36, v20
	v_add_u32_e32 v10, 40, v20
	v_add_u32_e32 v9, 44, v20
	v_add_u32_e32 v8, 48, v20
	v_add_u32_e32 v7, 52, v20
	v_add_u32_e32 v6, 56, v20
	v_add_u32_e32 v4, 60, v20
	v_mad_u32_u24 v5, v21, s9, v0
	s_cbranch_scc0 .LBB0_623
	s_add_i32 s3, s8, 0xfffff908
	s_lshl_b32 s2, s3, 6
	s_lshl_b32 s3, s3, 2
	s_and_b32 s2, s2, 0x3c0
	s_and_b32 s3, s3, 0x7fffffc0
	v_or_b32_e32 v0, s2, v21
	v_add_u32_e32 v26, s3, v20
	v_lshlrev_b32_e32 v0, 2, v0
	v_ashrrev_i32_e32 v27, 31, v26
	v_lshl_add_u64 v[24:25], s[60:61], 0, v[0:1]
	v_lshlrev_b64 v[26:27], 12, v[26:27]
	v_lshl_add_u64 v[26:27], v[24:25], 0, v[26:27]
	s_barrier
	flat_load_dword v206, v[26:27]
	v_add_u32_e32 v26, s3, v19
	v_ashrrev_i32_e32 v27, 31, v26
	v_lshlrev_b64 v[26:27], 12, v[26:27]
	v_lshl_add_u64 v[26:27], v[24:25], 0, v[26:27]
	v_mad_u64_u32 v[2:3], s[20:21], v19, s9, v[2:3]
	flat_load_dword v207, v[26:27]
	v_add_u32_e32 v26, s3, v18
	v_ashrrev_i32_e32 v27, 31, v26
	v_lshlrev_b64 v[26:27], 12, v[26:27]
	v_lshl_add_u64 v[26:27], v[24:25], 0, v[26:27]
	flat_load_dword v208, v[26:27]
	v_add_u32_e32 v26, s3, v17
	v_ashrrev_i32_e32 v27, 31, v26
	v_lshlrev_b64 v[26:27], 12, v[26:27]
	v_lshl_add_u64 v[26:27], v[24:25], 0, v[26:27]
	flat_load_dword v209, v[26:27]
	v_add_u32_e32 v26, s3, v16
	v_ashrrev_i32_e32 v27, 31, v26
	v_lshlrev_b64 v[26:27], 12, v[26:27]
	v_lshl_add_u64 v[26:27], v[24:25], 0, v[26:27]
	flat_load_dword v210, v[26:27]
	v_add_u32_e32 v26, s3, v15
	v_ashrrev_i32_e32 v27, 31, v26
	v_lshlrev_b64 v[26:27], 12, v[26:27]
	v_lshl_add_u64 v[26:27], v[24:25], 0, v[26:27]
	flat_load_dword v211, v[26:27]
	v_add_u32_e32 v26, s3, v14
	v_ashrrev_i32_e32 v27, 31, v26
	v_lshlrev_b64 v[26:27], 12, v[26:27]
	v_lshl_add_u64 v[26:27], v[24:25], 0, v[26:27]
	flat_load_dword v212, v[26:27]
	v_add_u32_e32 v26, s3, v13
	v_ashrrev_i32_e32 v27, 31, v26
	v_lshlrev_b64 v[26:27], 12, v[26:27]
	v_lshl_add_u64 v[26:27], v[24:25], 0, v[26:27]
	flat_load_dword v213, v[26:27]
	v_add_u32_e32 v26, s3, v12
	v_ashrrev_i32_e32 v27, 31, v26
	v_lshlrev_b64 v[26:27], 12, v[26:27]
	v_lshl_add_u64 v[26:27], v[24:25], 0, v[26:27]
	flat_load_dword v214, v[26:27]
	v_add_u32_e32 v26, s3, v11
	v_ashrrev_i32_e32 v27, 31, v26
	v_lshlrev_b64 v[26:27], 12, v[26:27]
	v_lshl_add_u64 v[26:27], v[24:25], 0, v[26:27]
	flat_load_dword v215, v[26:27]
	v_add_u32_e32 v26, s3, v10
	v_ashrrev_i32_e32 v27, 31, v26
	v_lshlrev_b64 v[26:27], 12, v[26:27]
	v_lshl_add_u64 v[26:27], v[24:25], 0, v[26:27]
	flat_load_dword v216, v[26:27]
	v_add_u32_e32 v26, s3, v9
	v_ashrrev_i32_e32 v27, 31, v26
	v_lshlrev_b64 v[26:27], 12, v[26:27]
	v_lshl_add_u64 v[26:27], v[24:25], 0, v[26:27]
	flat_load_dword v217, v[26:27]
	v_add_u32_e32 v26, s3, v8
	v_ashrrev_i32_e32 v27, 31, v26
	v_lshlrev_b64 v[26:27], 12, v[26:27]
	v_lshl_add_u64 v[26:27], v[24:25], 0, v[26:27]
	flat_load_dword v218, v[26:27]
	v_add_u32_e32 v26, s3, v7
	v_ashrrev_i32_e32 v27, 31, v26
	v_lshlrev_b64 v[26:27], 12, v[26:27]
	v_lshl_add_u64 v[26:27], v[24:25], 0, v[26:27]
	flat_load_dword v219, v[26:27]
	v_add_u32_e32 v26, s3, v6
	v_ashrrev_i32_e32 v27, 31, v26
	v_lshlrev_b64 v[26:27], 12, v[26:27]
	v_lshl_add_u64 v[26:27], v[24:25], 0, v[26:27]
	flat_load_dword v220, v[26:27]
	v_add_u32_e32 v26, s3, v4
	v_ashrrev_i32_e32 v27, 31, v26
	v_lshlrev_b64 v[26:27], 12, v[26:27]
	v_lshl_add_u64 v[24:25], v[24:25], 0, v[26:27]
	flat_load_dword v221, v[24:25]
	s_waitcnt vmcnt(15) lgkmcnt(0)
	ds_write_b32 v22, v206
	s_waitcnt vmcnt(14)
	ds_write_b32 v2, v207
	s_waitcnt vmcnt(13)
	ds_write_b32 v2, v208 offset:1040
	s_waitcnt vmcnt(12)
	ds_write_b32 v2, v209 offset:2080
	s_waitcnt vmcnt(11)
	ds_write_b32 v2, v210 offset:3120
	s_waitcnt vmcnt(10)
	ds_write_b32 v2, v211 offset:4160
	s_waitcnt vmcnt(9)
	ds_write_b32 v2, v212 offset:5200
	s_waitcnt vmcnt(8)
	ds_write_b32 v2, v213 offset:6240
	s_waitcnt vmcnt(7)
	ds_write_b32 v2, v214 offset:7280
	s_waitcnt vmcnt(6)
	ds_write_b32 v2, v215 offset:8320
	s_waitcnt vmcnt(5)
	ds_write_b32 v2, v216 offset:9360
	s_waitcnt vmcnt(4)
	ds_write_b32 v2, v217 offset:10400
	s_waitcnt vmcnt(3)
	ds_write_b32 v2, v218 offset:11440
	s_waitcnt vmcnt(2)
	ds_write_b32 v2, v219 offset:12480
	s_waitcnt vmcnt(1)
	ds_write_b32 v2, v220 offset:13520
	s_waitcnt vmcnt(0)
	ds_write_b32 v2, v221 offset:14560
	s_waitcnt lgkmcnt(0)
	s_barrier
; DI void transpose_job(const int tid_, const float* __restrict__ src, const float* __restrict__ scale, u16* __restrict__ dst, u16* __restrict__ dst2,
;                       int K, int N, int kt, int nt, char* s0, char* s1, char* s2) {
;     ...
; #pragma unroll
;   for (int i = 0; i < 16; ++i) {
;     int nl = (tid >> 6) + 4 * i, kl = tid & 63;
;     int k = kt * 64 + kl, n = nt * 64 + nl;
;     float v = tile[kl * 65 + nl];
;     float sc = scale ? scale[k] : 1.f;
;     dst[(size_t)n * K + k] = (u16)(pack2(v * sc, 0.f) & 0xffffu);
;     if (dst2) dst2[(size_t)n * K + k] = (u16)(pack2(v, 0.f) & 0xffffu);
;   }
	v_add_u32_e32 v2, s2, v20
	ds_read2_b32 v[24:25], v5 offset1:4
	ds_read2_b32 v[26:27], v5 offset0:8 offset1:12
	v_ashrrev_i32_e32 v3, 31, v2
	v_or_b32_e32 v0, s3, v21
	v_lshlrev_b64 v[2:3], 11, v[2:3]
	v_lshl_add_u64 v[2:3], s[14:15], 0, v[2:3]
	v_lshlrev_b32_e32 v0, 1, v0
	s_waitcnt lgkmcnt(1)
	v_cvt_pk_bf16_f32 v23, v24, s0
	v_lshl_add_u64 v[2:3], v[2:3], 0, v[0:1]
	flat_store_short v[2:3], v23
	v_add_u32_e32 v2, s2, v19
	v_ashrrev_i32_e32 v3, 31, v2
	v_lshlrev_b64 v[2:3], 11, v[2:3]
	v_lshl_add_u64 v[2:3], s[14:15], 0, v[2:3]
	v_cvt_pk_bf16_f32 v23, v25, s0
	v_lshl_add_u64 v[2:3], v[2:3], 0, v[0:1]
	flat_store_short v[2:3], v23
	v_add_u32_e32 v2, s2, v18
	v_ashrrev_i32_e32 v3, 31, v2
	v_lshlrev_b64 v[2:3], 11, v[2:3]
	v_lshl_add_u64 v[2:3], s[14:15], 0, v[2:3]
	s_waitcnt lgkmcnt(0)
	v_cvt_pk_bf16_f32 v23, v26, s0
	v_lshl_add_u64 v[2:3], v[2:3], 0, v[0:1]
	flat_store_short v[2:3], v23
	v_add_u32_e32 v2, s2, v17
	v_ashrrev_i32_e32 v3, 31, v2
	v_lshlrev_b64 v[2:3], 11, v[2:3]
	v_lshl_add_u64 v[2:3], s[14:15], 0, v[2:3]
	v_cvt_pk_bf16_f32 v23, v27, s0
	v_lshl_add_u64 v[2:3], v[2:3], 0, v[0:1]
	ds_read2_b32 v[24:25], v5 offset0:16 offset1:20
	flat_store_short v[2:3], v23
	v_add_u32_e32 v2, s2, v16
	v_ashrrev_i32_e32 v3, 31, v2
	v_lshlrev_b64 v[2:3], 11, v[2:3]
	v_lshl_add_u64 v[2:3], s[14:15], 0, v[2:3]
	s_waitcnt lgkmcnt(0)
	v_cvt_pk_bf16_f32 v23, v24, s0
	v_lshl_add_u64 v[2:3], v[2:3], 0, v[0:1]
	flat_store_short v[2:3], v23
	v_add_u32_e32 v2, s2, v15
	v_ashrrev_i32_e32 v3, 31, v2
	v_lshlrev_b64 v[2:3], 11, v[2:3]
	v_lshl_add_u64 v[2:3], s[14:15], 0, v[2:3]
	v_cvt_pk_bf16_f32 v23, v25, s0
	v_lshl_add_u64 v[2:3], v[2:3], 0, v[0:1]
	ds_read2_b32 v[24:25], v5 offset0:24 offset1:28
	flat_store_short v[2:3], v23
	v_add_u32_e32 v2, s2, v14
	v_ashrrev_i32_e32 v3, 31, v2
	v_lshlrev_b64 v[2:3], 11, v[2:3]
	v_lshl_add_u64 v[2:3], s[14:15], 0, v[2:3]
	s_waitcnt lgkmcnt(0)
	v_cvt_pk_bf16_f32 v23, v24, s0
	v_lshl_add_u64 v[2:3], v[2:3], 0, v[0:1]
	flat_store_short v[2:3], v23
	v_add_u32_e32 v2, s2, v13
	v_ashrrev_i32_e32 v3, 31, v2
	v_lshlrev_b64 v[2:3], 11, v[2:3]
	v_lshl_add_u64 v[2:3], s[14:15], 0, v[2:3]
	v_cvt_pk_bf16_f32 v23, v25, s0
	v_lshl_add_u64 v[2:3], v[2:3], 0, v[0:1]
	ds_read2_b32 v[24:25], v5 offset0:32 offset1:36
	flat_store_short v[2:3], v23
	v_add_u32_e32 v2, s2, v12
	v_ashrrev_i32_e32 v3, 31, v2
	v_lshlrev_b64 v[2:3], 11, v[2:3]
	v_lshl_add_u64 v[2:3], s[14:15], 0, v[2:3]
	s_waitcnt lgkmcnt(0)
	v_cvt_pk_bf16_f32 v23, v24, s0
	v_lshl_add_u64 v[2:3], v[2:3], 0, v[0:1]
	flat_store_short v[2:3], v23
	v_add_u32_e32 v2, s2, v11
	v_ashrrev_i32_e32 v3, 31, v2
	v_lshlrev_b64 v[2:3], 11, v[2:3]
	v_lshl_add_u64 v[2:3], s[14:15], 0, v[2:3]
	v_cvt_pk_bf16_f32 v23, v25, s0
	v_lshl_add_u64 v[2:3], v[2:3], 0, v[0:1]
	ds_read2_b32 v[26:27], v5 offset0:40 offset1:44
	ds_read2_b32 v[28:29], v5 offset0:48 offset1:52
	flat_store_short v[2:3], v23
	v_add_u32_e32 v2, s2, v10
	v_ashrrev_i32_e32 v3, 31, v2
	v_lshlrev_b64 v[2:3], 11, v[2:3]
	v_lshl_add_u64 v[2:3], s[14:15], 0, v[2:3]
	s_waitcnt lgkmcnt(0)
	v_cvt_pk_bf16_f32 v23, v26, s0
	v_lshl_add_u64 v[2:3], v[2:3], 0, v[0:1]
	flat_store_short v[2:3], v23
	v_add_u32_e32 v2, s2, v9
	v_ashrrev_i32_e32 v3, 31, v2
	v_lshlrev_b64 v[2:3], 11, v[2:3]
	v_lshl_add_u64 v[2:3], s[14:15], 0, v[2:3]
	v_cvt_pk_bf16_f32 v23, v27, s0
	v_lshl_add_u64 v[2:3], v[2:3], 0, v[0:1]
	flat_store_short v[2:3], v23
	v_add_u32_e32 v2, s2, v8
	v_ashrrev_i32_e32 v3, 31, v2
	v_lshlrev_b64 v[2:3], 11, v[2:3]
	v_lshl_add_u64 v[2:3], s[14:15], 0, v[2:3]
	v_cvt_pk_bf16_f32 v23, v28, s0
	v_lshl_add_u64 v[2:3], v[2:3], 0, v[0:1]
	flat_store_short v[2:3], v23
	v_add_u32_e32 v2, s2, v7
	v_ashrrev_i32_e32 v3, 31, v2
	v_lshlrev_b64 v[2:3], 11, v[2:3]
	v_lshl_add_u64 v[2:3], s[14:15], 0, v[2:3]
	v_cvt_pk_bf16_f32 v23, v29, s0
	v_lshl_add_u64 v[2:3], v[2:3], 0, v[0:1]
	ds_read2_b32 v[24:25], v5 offset0:56 offset1:60
	flat_store_short v[2:3], v23
	v_add_u32_e32 v2, s2, v6
	v_ashrrev_i32_e32 v3, 31, v2
	v_lshlrev_b64 v[2:3], 11, v[2:3]
	v_lshl_add_u64 v[2:3], s[14:15], 0, v[2:3]
	s_waitcnt lgkmcnt(0)
	v_cvt_pk_bf16_f32 v23, v24, s0
	v_lshl_add_u64 v[2:3], v[2:3], 0, v[0:1]
	flat_store_short v[2:3], v23
	v_add_u32_e32 v2, s2, v4
	v_ashrrev_i32_e32 v3, 31, v2
	v_lshlrev_b64 v[2:3], 11, v[2:3]
	v_lshl_add_u64 v[2:3], s[14:15], 0, v[2:3]
	v_cvt_pk_bf16_f32 v23, v25, s0
	v_lshl_add_u64 v[2:3], v[2:3], 0, v[0:1]
	flat_store_short v[2:3], v23
	s_mov_b64 s[2:3], 0
; DI void transpose_job(const int tid_, const float* __restrict__ src, const float* __restrict__ scale, u16* __restrict__ dst, u16* __restrict__ dst2,
;                       int K, int N, int kt, int nt, char* s0, char* s1, char* s2) {
;   float* tile = (float*)s0;
;   const int tid = tid_;
;   __syncthreads();
; #pragma unroll
;   for (int i = 0; i < 16; ++i) {
;     int kl = (tid >> 6) + 4 * i, nl = tid & 63;
;     int k = kt * 64 + kl, n = nt * 64 + nl;
;     tile[kl * 65 + nl] = (n < N) ? src[(size_t)k * N + n] : 0.f;
;   }
;   __syncthreads();
; DI void wprep_job(const int tid_, const Params& p, int l, int j, char* s0, char* s1, char* s2) {
;     ...
;     transpose_job(tid_, p.in[I_WB] + (size_t)l * 512 * 1024, nullptr, (u16*)(p.ws + WS_WB) + (size_t)l * 1024 * 512, nullptr, 512, 1024, q / 16, q % 16, s0, s1, s2);
.LBB0_623:
	s_andn2_b64 vcc, exec, s[2:3]
	s_cbranch_vccnz .LBB0_625
	s_add_i32 s3, s8, 0xfffff988
	s_lshl_b32 s2, s3, 6
	s_lshl_b32 s3, s3, 2
	s_and_b32 s2, s2, 0x3c0
	s_and_b32 s3, s3, 0x7fffffc0
	v_or_b32_e32 v0, s2, v21
	v_add_u32_e32 v24, s3, v20
	v_lshlrev_b32_e32 v0, 2, v0
	v_ashrrev_i32_e32 v25, 31, v24
	v_lshl_add_u64 v[2:3], s[62:63], 0, v[0:1]
	v_lshlrev_b64 v[24:25], 12, v[24:25]
	v_lshl_add_u64 v[24:25], v[2:3], 0, v[24:25]
	s_waitcnt lgkmcnt(0)
	s_barrier
	flat_load_dword v206, v[24:25]
	v_add_u32_e32 v24, s3, v19
	v_ashrrev_i32_e32 v25, 31, v24
	v_lshlrev_b64 v[24:25], 12, v[24:25]
	v_lshl_add_u64 v[24:25], v[2:3], 0, v[24:25]
	flat_load_dword v207, v[24:25]
	v_add_u32_e32 v24, s3, v18
	v_ashrrev_i32_e32 v25, 31, v24
	v_lshlrev_b64 v[24:25], 12, v[24:25]
	v_lshl_add_u64 v[24:25], v[2:3], 0, v[24:25]
	flat_load_dword v208, v[24:25]
	v_add_u32_e32 v24, s3, v17
	v_ashrrev_i32_e32 v25, 31, v24
	v_lshlrev_b64 v[24:25], 12, v[24:25]
	v_lshl_add_u64 v[24:25], v[2:3], 0, v[24:25]
	flat_load_dword v209, v[24:25]
	v_add_u32_e32 v24, s3, v16
	v_ashrrev_i32_e32 v25, 31, v24
	v_lshlrev_b64 v[24:25], 12, v[24:25]
	v_lshl_add_u64 v[24:25], v[2:3], 0, v[24:25]
	flat_load_dword v210, v[24:25]
	v_add_u32_e32 v24, s3, v15
	v_ashrrev_i32_e32 v25, 31, v24
	v_lshlrev_b64 v[24:25], 12, v[24:25]
	v_lshl_add_u64 v[24:25], v[2:3], 0, v[24:25]
	flat_load_dword v211, v[24:25]
	v_add_u32_e32 v24, s3, v14
	v_ashrrev_i32_e32 v25, 31, v24
	v_lshlrev_b64 v[24:25], 12, v[24:25]
	v_lshl_add_u64 v[24:25], v[2:3], 0, v[24:25]
	flat_load_dword v212, v[24:25]
	v_add_u32_e32 v24, s3, v13
	v_ashrrev_i32_e32 v25, 31, v24
	v_lshlrev_b64 v[24:25], 12, v[24:25]
	v_lshl_add_u64 v[24:25], v[2:3], 0, v[24:25]
	flat_load_dword v213, v[24:25]
	v_add_u32_e32 v24, s3, v12
	v_ashrrev_i32_e32 v25, 31, v24
	v_lshlrev_b64 v[24:25], 12, v[24:25]
	v_lshl_add_u64 v[24:25], v[2:3], 0, v[24:25]
	flat_load_dword v214, v[24:25]
	v_add_u32_e32 v24, s3, v11
	v_ashrrev_i32_e32 v25, 31, v24
	v_lshlrev_b64 v[24:25], 12, v[24:25]
	v_lshl_add_u64 v[24:25], v[2:3], 0, v[24:25]
	flat_load_dword v215, v[24:25]
	v_add_u32_e32 v24, s3, v10
	v_ashrrev_i32_e32 v25, 31, v24
	v_lshlrev_b64 v[24:25], 12, v[24:25]
	v_lshl_add_u64 v[24:25], v[2:3], 0, v[24:25]
	flat_load_dword v216, v[24:25]
	v_add_u32_e32 v24, s3, v9
	v_ashrrev_i32_e32 v25, 31, v24
	v_lshlrev_b64 v[24:25], 12, v[24:25]
	v_lshl_add_u64 v[24:25], v[2:3], 0, v[24:25]
	flat_load_dword v217, v[24:25]
	v_add_u32_e32 v24, s3, v8
	v_ashrrev_i32_e32 v25, 31, v24
	v_lshlrev_b64 v[24:25], 12, v[24:25]
	v_lshl_add_u64 v[24:25], v[2:3], 0, v[24:25]
	flat_load_dword v218, v[24:25]
	v_add_u32_e32 v24, s3, v7
	v_ashrrev_i32_e32 v25, 31, v24
	v_lshlrev_b64 v[24:25], 12, v[24:25]
	v_lshl_add_u64 v[24:25], v[2:3], 0, v[24:25]
	flat_load_dword v219, v[24:25]
	v_add_u32_e32 v24, s3, v6
	v_ashrrev_i32_e32 v25, 31, v24
	v_lshlrev_b64 v[24:25], 12, v[24:25]
	v_lshl_add_u64 v[24:25], v[2:3], 0, v[24:25]
	flat_load_dword v220, v[24:25]
	v_add_u32_e32 v24, s3, v4
	v_ashrrev_i32_e32 v25, 31, v24
	v_lshlrev_b64 v[24:25], 12, v[24:25]
	v_lshl_add_u64 v[2:3], v[2:3], 0, v[24:25]
	flat_load_dword v221, v[2:3]
	v_add_u32_e32 v2, s2, v20
	v_ashrrev_i32_e32 v3, 31, v2
	v_lshlrev_b64 v[2:3], 10, v[2:3]
	v_lshl_add_u64 v[2:3], s[42:43], 0, v[2:3]
	s_waitcnt vmcnt(15) lgkmcnt(0)
	ds_write_b32 v22, v206
	s_waitcnt vmcnt(14)
	ds_write_b32 v22, v207 offset:1040
	s_waitcnt vmcnt(13)
	ds_write_b32 v22, v208 offset:2080
	s_waitcnt vmcnt(12)
	ds_write_b32 v22, v209 offset:3120
	s_waitcnt vmcnt(11)
	ds_write_b32 v22, v210 offset:4160
	s_waitcnt vmcnt(10)
	ds_write_b32 v22, v211 offset:5200
	s_waitcnt vmcnt(9)
	ds_write_b32 v22, v212 offset:6240
	s_waitcnt vmcnt(8)
	ds_write_b32 v22, v213 offset:7280
	s_waitcnt vmcnt(7)
	ds_write_b32 v22, v214 offset:8320
	s_waitcnt vmcnt(6)
	ds_write_b32 v22, v215 offset:9360
	s_waitcnt vmcnt(5)
	ds_write_b32 v22, v216 offset:10400
	s_waitcnt vmcnt(4)
	ds_write_b32 v22, v217 offset:11440
	s_waitcnt vmcnt(3)
	ds_write_b32 v22, v218 offset:12480
	s_waitcnt vmcnt(2)
	ds_write_b32 v22, v219 offset:13520
	s_waitcnt vmcnt(1)
	ds_write_b32 v22, v220 offset:14560
	s_waitcnt vmcnt(0)
	ds_write_b32 v22, v221 offset:15600
	s_waitcnt lgkmcnt(0)
	s_barrier
; DI void transpose_job(const int tid_, const float* __restrict__ src, const float* __restrict__ scale, u16* __restrict__ dst, u16* __restrict__ dst2,
;                       int K, int N, int kt, int nt, char* s0, char* s1, char* s2) {
;     ...
; #pragma unroll
;   for (int i = 0; i < 16; ++i) {
;     int nl = (tid >> 6) + 4 * i, kl = tid & 63;
;     int k = kt * 64 + kl, n = nt * 64 + nl;
;     float v = tile[kl * 65 + nl];
;     float sc = scale ? scale[k] : 1.f;
;     dst[(size_t)n * K + k] = (u16)(pack2(v * sc, 0.f) & 0xffffu);
;     if (dst2) dst2[(size_t)n * K + k] = (u16)(pack2(v, 0.f) & 0xffffu);
;   }
	v_or_b32_e32 v0, s3, v21
	ds_read2_b32 v[20:21], v5 offset1:4
	ds_read2_b32 v[22:23], v5 offset0:8 offset1:12
	v_lshlrev_b32_e32 v0, 1, v0
	v_lshl_add_u64 v[2:3], v[2:3], 0, v[0:1]
	s_waitcnt lgkmcnt(1)
	v_cvt_pk_bf16_f32 v20, v20, s0
	flat_store_short v[2:3], v20
	v_add_u32_e32 v2, s2, v19
	v_ashrrev_i32_e32 v3, 31, v2
	v_lshlrev_b64 v[2:3], 10, v[2:3]
	v_lshl_add_u64 v[2:3], s[42:43], 0, v[2:3]
	v_cvt_pk_bf16_f32 v19, v21, s0
	v_lshl_add_u64 v[2:3], v[2:3], 0, v[0:1]
	flat_store_short v[2:3], v19
	v_add_u32_e32 v2, s2, v18
	v_ashrrev_i32_e32 v3, 31, v2
	v_lshlrev_b64 v[2:3], 10, v[2:3]
	v_lshl_add_u64 v[2:3], s[42:43], 0, v[2:3]
	s_waitcnt lgkmcnt(0)
	v_cvt_pk_bf16_f32 v18, v22, s0
	v_lshl_add_u64 v[2:3], v[2:3], 0, v[0:1]
	flat_store_short v[2:3], v18
	v_add_u32_e32 v2, s2, v17
	v_ashrrev_i32_e32 v3, 31, v2
	v_lshlrev_b64 v[2:3], 10, v[2:3]
	v_lshl_add_u64 v[2:3], s[42:43], 0, v[2:3]
	v_cvt_pk_bf16_f32 v17, v23, s0
	v_lshl_add_u64 v[2:3], v[2:3], 0, v[0:1]
	flat_store_short v[2:3], v17
	v_add_u32_e32 v2, s2, v16
	ds_read2_b32 v[16:17], v5 offset0:16 offset1:20
	v_ashrrev_i32_e32 v3, 31, v2
	v_lshlrev_b64 v[2:3], 10, v[2:3]
	v_lshl_add_u64 v[2:3], s[42:43], 0, v[2:3]
	v_lshl_add_u64 v[2:3], v[2:3], 0, v[0:1]
	s_waitcnt lgkmcnt(0)
	v_cvt_pk_bf16_f32 v16, v16, s0
	flat_store_short v[2:3], v16
	v_add_u32_e32 v2, s2, v15
	v_ashrrev_i32_e32 v3, 31, v2
	v_lshlrev_b64 v[2:3], 10, v[2:3]
	v_lshl_add_u64 v[2:3], s[42:43], 0, v[2:3]
	v_cvt_pk_bf16_f32 v15, v17, s0
	v_lshl_add_u64 v[2:3], v[2:3], 0, v[0:1]
	flat_store_short v[2:3], v15
	v_add_u32_e32 v2, s2, v14
	ds_read2_b32 v[14:15], v5 offset0:24 offset1:28
	v_ashrrev_i32_e32 v3, 31, v2
	v_lshlrev_b64 v[2:3], 10, v[2:3]
	v_lshl_add_u64 v[2:3], s[42:43], 0, v[2:3]
	v_lshl_add_u64 v[2:3], v[2:3], 0, v[0:1]
	s_waitcnt lgkmcnt(0)
	v_cvt_pk_bf16_f32 v14, v14, s0
	flat_store_short v[2:3], v14
	v_add_u32_e32 v2, s2, v13
	v_ashrrev_i32_e32 v3, 31, v2
	v_lshlrev_b64 v[2:3], 10, v[2:3]
	v_lshl_add_u64 v[2:3], s[42:43], 0, v[2:3]
	v_cvt_pk_bf16_f32 v13, v15, s0
	v_lshl_add_u64 v[2:3], v[2:3], 0, v[0:1]
	flat_store_short v[2:3], v13
	v_add_u32_e32 v2, s2, v12
	ds_read2_b32 v[12:13], v5 offset0:32 offset1:36
	v_ashrrev_i32_e32 v3, 31, v2
	v_lshlrev_b64 v[2:3], 10, v[2:3]
	v_lshl_add_u64 v[2:3], s[42:43], 0, v[2:3]
	v_lshl_add_u64 v[2:3], v[2:3], 0, v[0:1]
	s_waitcnt lgkmcnt(0)
	v_cvt_pk_bf16_f32 v12, v12, s0
	flat_store_short v[2:3], v12
	v_add_u32_e32 v2, s2, v11
	v_ashrrev_i32_e32 v3, 31, v2
	v_lshlrev_b64 v[2:3], 10, v[2:3]
	v_lshl_add_u64 v[2:3], s[42:43], 0, v[2:3]
	v_cvt_pk_bf16_f32 v11, v13, s0
	v_lshl_add_u64 v[2:3], v[2:3], 0, v[0:1]
	ds_read2_b32 v[14:15], v5 offset0:40 offset1:44
	ds_read2_b32 v[16:17], v5 offset0:48 offset1:52
	flat_store_short v[2:3], v11
	v_add_u32_e32 v2, s2, v10
	v_ashrrev_i32_e32 v3, 31, v2
	v_lshlrev_b64 v[2:3], 10, v[2:3]
	v_lshl_add_u64 v[2:3], s[42:43], 0, v[2:3]
	s_waitcnt lgkmcnt(0)
	v_cvt_pk_bf16_f32 v10, v14, s0
	v_lshl_add_u64 v[2:3], v[2:3], 0, v[0:1]
	flat_store_short v[2:3], v10
	v_add_u32_e32 v2, s2, v9
	v_ashrrev_i32_e32 v3, 31, v2
	v_lshlrev_b64 v[2:3], 10, v[2:3]
	v_lshl_add_u64 v[2:3], s[42:43], 0, v[2:3]
	v_cvt_pk_bf16_f32 v9, v15, s0
	v_lshl_add_u64 v[2:3], v[2:3], 0, v[0:1]
	flat_store_short v[2:3], v9
	v_add_u32_e32 v2, s2, v8
	v_ashrrev_i32_e32 v3, 31, v2
	v_lshlrev_b64 v[2:3], 10, v[2:3]
	v_lshl_add_u64 v[2:3], s[42:43], 0, v[2:3]
	v_cvt_pk_bf16_f32 v8, v16, s0
	v_lshl_add_u64 v[2:3], v[2:3], 0, v[0:1]
	flat_store_short v[2:3], v8
	v_add_u32_e32 v2, s2, v7
	v_ashrrev_i32_e32 v3, 31, v2
	v_lshlrev_b64 v[2:3], 10, v[2:3]
	v_lshl_add_u64 v[2:3], s[42:43], 0, v[2:3]
	v_cvt_pk_bf16_f32 v7, v17, s0
	v_lshl_add_u64 v[2:3], v[2:3], 0, v[0:1]
	flat_store_short v[2:3], v7
	v_add_u32_e32 v2, s2, v6
	ds_read2_b32 v[6:7], v5 offset0:56 offset1:60
	v_ashrrev_i32_e32 v3, 31, v2
	v_lshlrev_b64 v[2:3], 10, v[2:3]
	v_lshl_add_u64 v[2:3], s[42:43], 0, v[2:3]
	v_lshl_add_u64 v[2:3], v[2:3], 0, v[0:1]
	s_waitcnt lgkmcnt(0)
	v_cvt_pk_bf16_f32 v5, v6, s0
	flat_store_short v[2:3], v5
	v_add_u32_e32 v2, s2, v4
	v_ashrrev_i32_e32 v3, 31, v2
	v_lshlrev_b64 v[2:3], 10, v[2:3]
	v_lshl_add_u64 v[2:3], s[42:43], 0, v[2:3]
	v_cvt_pk_bf16_f32 v4, v7, s0
	v_lshl_add_u64 v[2:3], v[2:3], 0, v[0:1]
	flat_store_short v[2:3], v4

; DI void transpose_job(const int tid_, const float* __restrict__ src, const float* __restrict__ scale, u16* __restrict__ dst, u16* __restrict__ dst2,
;                       int K, int N, int kt, int nt, char* s0, char* s1, char* s2) {
;   float* tile = (float*)s0;
;   const int tid = tid_;
;   __syncthreads();
; #pragma unroll
;   for (int i = 0; i < 16; ++i) {
;     int kl = (tid >> 6) + 4 * i, nl = tid & 63;
;     int k = kt * 64 + kl, n = nt * 64 + nl;
;     tile[kl * 65 + nl] = (n < N) ? src[(size_t)k * N + n] : 0.f;
;   }
;   __syncthreads();
; DI void wprep_job(const int tid_, const Params& p, int l, int j, char* s0, char* s1, char* s2) {
;     ...
;     transpose_job(tid_, p.in[I_WA] + (size_t)l * 512 * 1024, nullptr, (u16*)(p.ws + WS_WA) + (size_t)l * 1024 * 512, nullptr, 512, 1024, q / 16, q % 16, s0, s1, s2);
.LBB0_626:
	s_andn2_b64 vcc, exec, s[2:3]
	s_cbranch_vccnz .LBB0_628
	s_add_i32 s3, s8, 0xfffffa08
	s_lshl_b32 s2, s3, 6
	s_lshl_b32 s3, s3, 2
	v_ashrrev_i32_e32 v6, 6, v35
	v_and_b32_e32 v7, 63, v34
	s_and_b32 s2, s2, 0x3c0
	s_and_b32 s3, s3, 0x7fffffc0
	v_or_b32_e32 v0, s2, v7
	v_readlane_b32 s20, v255, 1
	v_add_u32_e32 v4, s3, v6
	v_lshlrev_b32_e32 v0, 2, v0
	v_readlane_b32 s21, v255, 2
	v_ashrrev_i32_e32 v5, 31, v4
	v_lshlrev_b64 v[4:5], 12, v[4:5]
	v_lshl_add_u64 v[2:3], s[20:21], 0, v[0:1]
	v_lshl_add_u64 v[4:5], v[2:3], 0, v[4:5]
	s_waitcnt lgkmcnt(0)
	s_barrier
	flat_load_dword v0, v[4:5]
	s_movk_i32 s9, 0x104
	v_mul_lo_u32 v4, v6, s9
	v_add_u32_e32 v9, 4, v6
	v_lshl_add_u32 v8, v7, 2, v4
	v_add_u32_e32 v4, s3, v9
	v_ashrrev_i32_e32 v5, 31, v4
	v_lshlrev_b64 v[4:5], 12, v[4:5]
	v_lshl_add_u64 v[4:5], v[2:3], 0, v[4:5]
	v_add_u32_e32 v10, 8, v6
	v_add_u32_e32 v11, 12, v6
	v_add_u32_e32 v12, 16, v6
	v_add_u32_e32 v13, 20, v6
	v_add_u32_e32 v14, 24, v6
	v_add_u32_e32 v15, 28, v6
	v_add_u32_e32 v16, 32, v6
	v_add_u32_e32 v17, 36, v6
	v_add_u32_e32 v18, 40, v6
	v_add_u32_e32 v19, 44, v6
	v_add_u32_e32 v20, 48, v6
	v_add_u32_e32 v21, 52, v6
	v_add_u32_e32 v22, 56, v6
	v_add_u32_e32 v23, 60, v6
	s_waitcnt vmcnt(0) lgkmcnt(0)
	ds_write_b32 v8, v0
	flat_load_dword v206, v[4:5]
	v_add_u32_e32 v4, s3, v10
	v_ashrrev_i32_e32 v5, 31, v4
	v_lshlrev_b64 v[4:5], 12, v[4:5]
	v_lshl_add_u64 v[4:5], v[2:3], 0, v[4:5]
	flat_load_dword v207, v[4:5]
	v_add_u32_e32 v4, s3, v11
	v_ashrrev_i32_e32 v5, 31, v4
	v_lshlrev_b64 v[4:5], 12, v[4:5]
	v_lshl_add_u64 v[4:5], v[2:3], 0, v[4:5]
	flat_load_dword v208, v[4:5]
	v_add_u32_e32 v4, s3, v12
	v_ashrrev_i32_e32 v5, 31, v4
	v_lshlrev_b64 v[4:5], 12, v[4:5]
	v_lshl_add_u64 v[4:5], v[2:3], 0, v[4:5]
	flat_load_dword v209, v[4:5]
	v_add_u32_e32 v4, s3, v13
	v_ashrrev_i32_e32 v5, 31, v4
	v_lshlrev_b64 v[4:5], 12, v[4:5]
	v_lshl_add_u64 v[4:5], v[2:3], 0, v[4:5]
	flat_load_dword v210, v[4:5]
	v_add_u32_e32 v4, s3, v14
	v_ashrrev_i32_e32 v5, 31, v4
	v_lshlrev_b64 v[4:5], 12, v[4:5]
	v_lshl_add_u64 v[4:5], v[2:3], 0, v[4:5]
	flat_load_dword v211, v[4:5]
	v_add_u32_e32 v4, s3, v15
	v_ashrrev_i32_e32 v5, 31, v4
	v_lshlrev_b64 v[4:5], 12, v[4:5]
	v_lshl_add_u64 v[4:5], v[2:3], 0, v[4:5]
	flat_load_dword v212, v[4:5]
	v_add_u32_e32 v4, s3, v16
	v_ashrrev_i32_e32 v5, 31, v4
	v_lshlrev_b64 v[4:5], 12, v[4:5]
	v_lshl_add_u64 v[4:5], v[2:3], 0, v[4:5]
	flat_load_dword v213, v[4:5]
	v_add_u32_e32 v4, s3, v17
	v_ashrrev_i32_e32 v5, 31, v4
	v_lshlrev_b64 v[4:5], 12, v[4:5]
	v_lshl_add_u64 v[4:5], v[2:3], 0, v[4:5]
	flat_load_dword v214, v[4:5]
	v_add_u32_e32 v4, s3, v18
	v_ashrrev_i32_e32 v5, 31, v4
	v_lshlrev_b64 v[4:5], 12, v[4:5]
	v_lshl_add_u64 v[4:5], v[2:3], 0, v[4:5]
	flat_load_dword v215, v[4:5]
	v_add_u32_e32 v4, s3, v19
	v_ashrrev_i32_e32 v5, 31, v4
	v_lshlrev_b64 v[4:5], 12, v[4:5]
	v_lshl_add_u64 v[4:5], v[2:3], 0, v[4:5]
	flat_load_dword v216, v[4:5]
	v_add_u32_e32 v4, s3, v20
	v_ashrrev_i32_e32 v5, 31, v4
	v_lshlrev_b64 v[4:5], 12, v[4:5]
	v_lshl_add_u64 v[4:5], v[2:3], 0, v[4:5]
	flat_load_dword v217, v[4:5]
	v_add_u32_e32 v4, s3, v21
	v_ashrrev_i32_e32 v5, 31, v4
	v_lshlrev_b64 v[4:5], 12, v[4:5]
	v_lshl_add_u64 v[4:5], v[2:3], 0, v[4:5]
	flat_load_dword v218, v[4:5]
	v_add_u32_e32 v4, s3, v22
	v_ashrrev_i32_e32 v5, 31, v4
	v_lshlrev_b64 v[4:5], 12, v[4:5]
	v_lshl_add_u64 v[4:5], v[2:3], 0, v[4:5]
	flat_load_dword v219, v[4:5]
	v_add_u32_e32 v4, s3, v23
	v_ashrrev_i32_e32 v5, 31, v4
	v_lshlrev_b64 v[4:5], 12, v[4:5]
	v_lshl_add_u64 v[2:3], v[2:3], 0, v[4:5]
	flat_load_dword v220, v[2:3]
	v_lshlrev_b32_e32 v3, 2, v6
	v_mad_u32_u24 v24, v7, s9, v3
	v_add_u32_e32 v2, s2, v6
	v_ashrrev_i32_e32 v3, 31, v2
	v_lshlrev_b64 v[2:3], 10, v[2:3]
	v_lshl_add_u64 v[2:3], s[46:47], 0, v[2:3]
	s_waitcnt vmcnt(14) lgkmcnt(0)
	ds_write_b32 v8, v206 offset:1040
	s_waitcnt vmcnt(13)
	ds_write_b32 v8, v207 offset:2080
	s_waitcnt vmcnt(12)
	ds_write_b32 v8, v208 offset:3120
	s_waitcnt vmcnt(11)
	ds_write_b32 v8, v209 offset:4160
	s_waitcnt vmcnt(10)
	ds_write_b32 v8, v210 offset:5200
	s_waitcnt vmcnt(9)
	ds_write_b32 v8, v211 offset:6240
	s_waitcnt vmcnt(8)
	ds_write_b32 v8, v212 offset:7280
	s_waitcnt vmcnt(7)
	ds_write_b32 v8, v213 offset:8320
	s_waitcnt vmcnt(6)
	ds_write_b32 v8, v214 offset:9360
	s_waitcnt vmcnt(5)
	ds_write_b32 v8, v215 offset:10400
	s_waitcnt vmcnt(4)
	ds_write_b32 v8, v216 offset:11440
	s_waitcnt vmcnt(3)
	ds_write_b32 v8, v217 offset:12480
	s_waitcnt vmcnt(2)
	ds_write_b32 v8, v218 offset:13520
	s_waitcnt vmcnt(1)
	ds_write_b32 v8, v219 offset:14560
	s_waitcnt vmcnt(0)
	ds_write_b32 v8, v220 offset:15600
	s_waitcnt lgkmcnt(0)
	s_barrier
; DI void transpose_job(const int tid_, const float* __restrict__ src, const float* __restrict__ scale, u16* __restrict__ dst, u16* __restrict__ dst2,
;                       int K, int N, int kt, int nt, char* s0, char* s1, char* s2) {
;     ...
; #pragma unroll
;   for (int i = 0; i < 16; ++i) {
;     int nl = (tid >> 6) + 4 * i, kl = tid & 63;
;     int k = kt * 64 + kl, n = nt * 64 + nl;
;     float v = tile[kl * 65 + nl];
;     float sc = scale ? scale[k] : 1.f;
;     dst[(size_t)n * K + k] = (u16)(pack2(v * sc, 0.f) & 0xffffu);
;     if (dst2) dst2[(size_t)n * K + k] = (u16)(pack2(v, 0.f) & 0xffffu);
;   }
	v_or_b32_e32 v0, s3, v7
	ds_read2_b32 v[4:5], v24 offset1:4
	ds_read2_b32 v[6:7], v24 offset0:8 offset1:12
	v_lshlrev_b32_e32 v0, 1, v0
	v_lshl_add_u64 v[2:3], v[2:3], 0, v[0:1]
	s_waitcnt lgkmcnt(1)
	v_cvt_pk_bf16_f32 v4, v4, s0
	flat_store_short v[2:3], v4
	v_add_u32_e32 v2, s2, v9
	v_ashrrev_i32_e32 v3, 31, v2
	v_lshlrev_b64 v[2:3], 10, v[2:3]
	v_lshl_add_u64 v[2:3], s[46:47], 0, v[2:3]
	v_cvt_pk_bf16_f32 v4, v5, s0
	v_lshl_add_u64 v[2:3], v[2:3], 0, v[0:1]
	flat_store_short v[2:3], v4
	v_add_u32_e32 v2, s2, v10
	v_ashrrev_i32_e32 v3, 31, v2
	v_lshlrev_b64 v[2:3], 10, v[2:3]
	v_lshl_add_u64 v[2:3], s[46:47], 0, v[2:3]
	s_waitcnt lgkmcnt(0)
	v_cvt_pk_bf16_f32 v4, v6, s0
	v_lshl_add_u64 v[2:3], v[2:3], 0, v[0:1]
	flat_store_short v[2:3], v4
	v_add_u32_e32 v2, s2, v11
	v_ashrrev_i32_e32 v3, 31, v2
	v_lshlrev_b64 v[2:3], 10, v[2:3]
	v_lshl_add_u64 v[2:3], s[46:47], 0, v[2:3]
	v_cvt_pk_bf16_f32 v4, v7, s0
	v_lshl_add_u64 v[2:3], v[2:3], 0, v[0:1]
	flat_store_short v[2:3], v4
	ds_read2_b32 v[4:5], v24 offset0:16 offset1:20
	v_add_u32_e32 v2, s2, v12
	v_ashrrev_i32_e32 v3, 31, v2
	v_lshlrev_b64 v[2:3], 10, v[2:3]
	v_lshl_add_u64 v[2:3], s[46:47], 0, v[2:3]
	s_waitcnt lgkmcnt(0)
	v_cvt_pk_bf16_f32 v4, v4, s0
	v_lshl_add_u64 v[2:3], v[2:3], 0, v[0:1]
	flat_store_short v[2:3], v4
	v_add_u32_e32 v2, s2, v13
	v_ashrrev_i32_e32 v3, 31, v2
	v_lshlrev_b64 v[2:3], 10, v[2:3]
	v_lshl_add_u64 v[2:3], s[46:47], 0, v[2:3]
	v_cvt_pk_bf16_f32 v4, v5, s0
	v_lshl_add_u64 v[2:3], v[2:3], 0, v[0:1]
	flat_store_short v[2:3], v4
	ds_read2_b32 v[4:5], v24 offset0:24 offset1:28
	v_add_u32_e32 v2, s2, v14
	v_ashrrev_i32_e32 v3, 31, v2
	v_lshlrev_b64 v[2:3], 10, v[2:3]
	v_lshl_add_u64 v[2:3], s[46:47], 0, v[2:3]
	s_waitcnt lgkmcnt(0)
	v_cvt_pk_bf16_f32 v4, v4, s0
	v_lshl_add_u64 v[2:3], v[2:3], 0, v[0:1]
	flat_store_short v[2:3], v4
	v_add_u32_e32 v2, s2, v15
	v_ashrrev_i32_e32 v3, 31, v2
	v_lshlrev_b64 v[2:3], 10, v[2:3]
	v_lshl_add_u64 v[2:3], s[46:47], 0, v[2:3]
	v_cvt_pk_bf16_f32 v4, v5, s0
	v_lshl_add_u64 v[2:3], v[2:3], 0, v[0:1]
	flat_store_short v[2:3], v4
	ds_read2_b32 v[4:5], v24 offset0:32 offset1:36
	v_add_u32_e32 v2, s2, v16
	v_ashrrev_i32_e32 v3, 31, v2
	v_lshlrev_b64 v[2:3], 10, v[2:3]
	v_lshl_add_u64 v[2:3], s[46:47], 0, v[2:3]
	s_waitcnt lgkmcnt(0)
	v_cvt_pk_bf16_f32 v4, v4, s0
	v_lshl_add_u64 v[2:3], v[2:3], 0, v[0:1]
	flat_store_short v[2:3], v4
	v_add_u32_e32 v2, s2, v17
	v_ashrrev_i32_e32 v3, 31, v2
	v_lshlrev_b64 v[2:3], 10, v[2:3]
	v_lshl_add_u64 v[2:3], s[46:47], 0, v[2:3]
	v_cvt_pk_bf16_f32 v4, v5, s0
	v_lshl_add_u64 v[2:3], v[2:3], 0, v[0:1]
	ds_read2_b32 v[6:7], v24 offset0:40 offset1:44
	ds_read2_b32 v[8:9], v24 offset0:48 offset1:52
	flat_store_short v[2:3], v4
	v_add_u32_e32 v2, s2, v18
	v_ashrrev_i32_e32 v3, 31, v2
	v_lshlrev_b64 v[2:3], 10, v[2:3]
	v_lshl_add_u64 v[2:3], s[46:47], 0, v[2:3]
	s_waitcnt lgkmcnt(0)
	v_cvt_pk_bf16_f32 v4, v6, s0
	v_lshl_add_u64 v[2:3], v[2:3], 0, v[0:1]
	flat_store_short v[2:3], v4
	v_add_u32_e32 v2, s2, v19
	v_ashrrev_i32_e32 v3, 31, v2
	v_lshlrev_b64 v[2:3], 10, v[2:3]
	v_lshl_add_u64 v[2:3], s[46:47], 0, v[2:3]
	v_cvt_pk_bf16_f32 v4, v7, s0
	v_lshl_add_u64 v[2:3], v[2:3], 0, v[0:1]
	flat_store_short v[2:3], v4
	v_add_u32_e32 v2, s2, v20
	v_ashrrev_i32_e32 v3, 31, v2
	v_lshlrev_b64 v[2:3], 10, v[2:3]
	v_lshl_add_u64 v[2:3], s[46:47], 0, v[2:3]
	v_cvt_pk_bf16_f32 v4, v8, s0
	v_lshl_add_u64 v[2:3], v[2:3], 0, v[0:1]
	flat_store_short v[2:3], v4
	v_add_u32_e32 v2, s2, v21
	v_ashrrev_i32_e32 v3, 31, v2
	v_lshlrev_b64 v[2:3], 10, v[2:3]
	v_lshl_add_u64 v[2:3], s[46:47], 0, v[2:3]
	v_cvt_pk_bf16_f32 v4, v9, s0
	v_lshl_add_u64 v[2:3], v[2:3], 0, v[0:1]
	flat_store_short v[2:3], v4
	ds_read2_b32 v[4:5], v24 offset0:56 offset1:60
	v_add_u32_e32 v2, s2, v22
	v_ashrrev_i32_e32 v3, 31, v2
	v_lshlrev_b64 v[2:3], 10, v[2:3]
	v_lshl_add_u64 v[2:3], s[46:47], 0, v[2:3]
	s_waitcnt lgkmcnt(0)
	v_cvt_pk_bf16_f32 v4, v4, s0
	v_lshl_add_u64 v[2:3], v[2:3], 0, v[0:1]
	flat_store_short v[2:3], v4
	v_add_u32_e32 v2, s2, v23
	v_ashrrev_i32_e32 v3, 31, v2
	v_lshlrev_b64 v[2:3], 10, v[2:3]
	v_lshl_add_u64 v[2:3], s[46:47], 0, v[2:3]
	v_cvt_pk_bf16_f32 v4, v5, s0
	v_lshl_add_u64 v[2:3], v[2:3], 0, v[0:1]
	flat_store_short v[2:3], v4

; DI void transpose_job(const int tid_, const float* __restrict__ src, const float* __restrict__ scale, u16* __restrict__ dst, u16* __restrict__ dst2,
;                       int K, int N, int kt, int nt, char* s0, char* s1, char* s2) {
;   float* tile = (float*)s0;
;   const int tid = tid_;
;   __syncthreads();
; #pragma unroll
;   for (int i = 0; i < 16; ++i) {
;     int kl = (tid >> 6) + 4 * i, nl = tid & 63;
;     int k = kt * 64 + kl, n = nt * 64 + nl;
;     tile[kl * 65 + nl] = (n < N) ? src[(size_t)k * N + n] : 0.f;
;   }
;   __syncthreads();
; #pragma unroll
;   for (int i = 0; i < 16; ++i) {
;     int nl = (tid >> 6) + 4 * i, kl = tid & 63;
;     int k = kt * 64 + kl, n = nt * 64 + nl;
;     float v = tile[kl * 65 + nl];
;     float sc = scale ? scale[k] : 1.f;
; DI void wprep_job(const int tid_, const Params& p, int l, int j, char* s0, char* s1, char* s2) {
;     ...
;     int q = j - 1464;
;     transpose_job(tid_, p.in[I_WUKV] + (size_t)l * 256 * 1024, p.in[I_KVNORM] + l * 256, (u16*)(p.ws + WS_WKVF) + (size_t)l * 1024 * 256,
;                   (u16*)(p.ws + WS_WKVP) + (size_t)l * 1024 * 256, 256, 1024, q / 16, q % 16, s0, s1, s2);
.LBB0_629:
	s_andn2_b64 vcc, exec, s[2:3]
	s_cbranch_vccnz .LBB0_663
	s_add_i32 s3, s8, 0xfffffa48
	s_lshl_b32 s2, s3, 6
	s_lshl_b32 s3, s3, 2
	v_ashrrev_i32_e32 v19, 6, v35
	v_and_b32_e32 v13, 63, v34
	s_and_b32 s2, s2, 0x3c0
	s_and_b32 s3, s3, 0x7fffffc0
	v_or_b32_e32 v0, s2, v13
	v_readlane_b32 s20, v255, 3
	v_add_u32_e32 v4, s3, v19
	v_lshlrev_b32_e32 v0, 2, v0
	v_readlane_b32 s21, v255, 4
	v_ashrrev_i32_e32 v5, 31, v4
	v_lshlrev_b64 v[4:5], 12, v[4:5]
	v_lshl_add_u64 v[2:3], s[20:21], 0, v[0:1]
	v_lshl_add_u64 v[4:5], v[2:3], 0, v[4:5]
	s_waitcnt lgkmcnt(0)
	s_barrier
	flat_load_dword v0, v[4:5]
	s_movk_i32 s9, 0x104
	v_mul_lo_u32 v4, v19, s9
	v_add_u32_e32 v20, 4, v19
	v_lshl_add_u32 v21, v13, 2, v4
	v_add_u32_e32 v4, s3, v20
	v_ashrrev_i32_e32 v5, 31, v4
	v_lshlrev_b64 v[4:5], 12, v[4:5]
	v_lshl_add_u64 v[4:5], v[2:3], 0, v[4:5]
	v_add_u32_e32 v18, 8, v19
	v_add_u32_e32 v17, 12, v19
	v_add_u32_e32 v16, 16, v19
	v_add_u32_e32 v15, 20, v19
	v_add_u32_e32 v14, 24, v19
	v_add_u32_e32 v11, 28, v19
	v_add_u32_e32 v12, 32, v19
	v_add_u32_e32 v10, 36, v19
	v_add_u32_e32 v9, 40, v19
	v_add_u32_e32 v8, 44, v19
	v_add_u32_e32 v7, 48, v19
	v_add_u32_e32 v6, 52, v19
	v_readlane_b32 s20, v255, 5
	v_readlane_b32 s21, v255, 6
	s_waitcnt vmcnt(0) lgkmcnt(0)
	ds_write_b32 v21, v0
	flat_load_dword v206, v[4:5]
	v_add_u32_e32 v4, s3, v18
	v_ashrrev_i32_e32 v5, 31, v4
	v_lshlrev_b64 v[4:5], 12, v[4:5]
	v_lshl_add_u64 v[4:5], v[2:3], 0, v[4:5]
	flat_load_dword v207, v[4:5]
	v_add_u32_e32 v4, s3, v17
	v_ashrrev_i32_e32 v5, 31, v4
	v_lshlrev_b64 v[4:5], 12, v[4:5]
	v_lshl_add_u64 v[4:5], v[2:3], 0, v[4:5]
	flat_load_dword v208, v[4:5]
	v_add_u32_e32 v4, s3, v16
	v_ashrrev_i32_e32 v5, 31, v4
	v_lshlrev_b64 v[4:5], 12, v[4:5]
	v_lshl_add_u64 v[4:5], v[2:3], 0, v[4:5]
	flat_load_dword v209, v[4:5]
	v_add_u32_e32 v4, s3, v15
	v_ashrrev_i32_e32 v5, 31, v4
	v_lshlrev_b64 v[4:5], 12, v[4:5]
	v_lshl_add_u64 v[4:5], v[2:3], 0, v[4:5]
	flat_load_dword v210, v[4:5]
	v_add_u32_e32 v4, s3, v14
	v_ashrrev_i32_e32 v5, 31, v4
	v_lshlrev_b64 v[4:5], 12, v[4:5]
	v_lshl_add_u64 v[4:5], v[2:3], 0, v[4:5]
	flat_load_dword v211, v[4:5]
	v_add_u32_e32 v4, s3, v11
	v_ashrrev_i32_e32 v5, 31, v4
	v_lshlrev_b64 v[4:5], 12, v[4:5]
	v_lshl_add_u64 v[4:5], v[2:3], 0, v[4:5]
	flat_load_dword v212, v[4:5]
	v_add_u32_e32 v4, s3, v12
	v_ashrrev_i32_e32 v5, 31, v4
	v_lshlrev_b64 v[4:5], 12, v[4:5]
	v_lshl_add_u64 v[4:5], v[2:3], 0, v[4:5]
	flat_load_dword v213, v[4:5]
	v_add_u32_e32 v4, s3, v10
	v_ashrrev_i32_e32 v5, 31, v4
	v_lshlrev_b64 v[4:5], 12, v[4:5]
	v_lshl_add_u64 v[4:5], v[2:3], 0, v[4:5]
	flat_load_dword v214, v[4:5]
	v_add_u32_e32 v4, s3, v9
	v_ashrrev_i32_e32 v5, 31, v4
	v_lshlrev_b64 v[4:5], 12, v[4:5]
	v_lshl_add_u64 v[4:5], v[2:3], 0, v[4:5]
	flat_load_dword v215, v[4:5]
	v_add_u32_e32 v4, s3, v8
	v_ashrrev_i32_e32 v5, 31, v4
	v_lshlrev_b64 v[4:5], 12, v[4:5]
	v_lshl_add_u64 v[4:5], v[2:3], 0, v[4:5]
	flat_load_dword v216, v[4:5]
	v_add_u32_e32 v4, s3, v7
	v_ashrrev_i32_e32 v5, 31, v4
	v_lshlrev_b64 v[4:5], 12, v[4:5]
	v_lshl_add_u64 v[4:5], v[2:3], 0, v[4:5]
	flat_load_dword v217, v[4:5]
	v_add_u32_e32 v4, s3, v6
	v_ashrrev_i32_e32 v5, 31, v4
	v_lshlrev_b64 v[4:5], 12, v[4:5]
	v_lshl_add_u64 v[4:5], v[2:3], 0, v[4:5]
	flat_load_dword v218, v[4:5]
	v_add_u32_e32 v5, 56, v19
	v_add_u32_e32 v22, s3, v5
	v_ashrrev_i32_e32 v23, 31, v22
	v_lshlrev_b64 v[22:23], 12, v[22:23]
	v_lshl_add_u64 v[22:23], v[2:3], 0, v[22:23]
	v_add_u32_e32 v4, 60, v19
	flat_load_dword v219, v[22:23]
	v_add_u32_e32 v22, s3, v4
	v_ashrrev_i32_e32 v23, 31, v22
	v_lshlrev_b64 v[22:23], 12, v[22:23]
	v_lshl_add_u64 v[2:3], v[2:3], 0, v[22:23]
	flat_load_dword v220, v[2:3]
	s_waitcnt vmcnt(14) lgkmcnt(0)
	ds_write_b32 v21, v206 offset:1040
	s_waitcnt vmcnt(13)
	ds_write_b32 v21, v207 offset:2080
	s_waitcnt vmcnt(12)
	ds_write_b32 v21, v208 offset:3120
	s_waitcnt vmcnt(11)
	ds_write_b32 v21, v209 offset:4160
	s_waitcnt vmcnt(10)
	ds_write_b32 v21, v210 offset:5200
	s_waitcnt vmcnt(9)
	ds_write_b32 v21, v211 offset:6240
	s_waitcnt vmcnt(8)
	ds_write_b32 v21, v212 offset:7280
	s_waitcnt vmcnt(7)
	ds_write_b32 v21, v213 offset:8320
	s_waitcnt vmcnt(6)
	ds_write_b32 v21, v214 offset:9360
	s_waitcnt vmcnt(5)
	ds_write_b32 v21, v215 offset:10400
	s_waitcnt vmcnt(4)
	ds_write_b32 v21, v216 offset:11440
	s_waitcnt vmcnt(3)
	ds_write_b32 v21, v217 offset:12480
	s_waitcnt vmcnt(2)
	ds_write_b32 v21, v218 offset:13520
	s_waitcnt vmcnt(1)
	ds_write_b32 v21, v219 offset:14560
	s_waitcnt vmcnt(0)
	ds_write_b32 v21, v220 offset:15600
	v_lshlrev_b32_e32 v21, 2, v19
	v_or_b32_e32 v0, s3, v13
	v_mad_u32_u24 v13, v13, s9, v21
	s_waitcnt lgkmcnt(0)
	s_barrier
	ds_read_b32 v22, v13
	v_lshl_add_u64 v[2:3], v[0:1], 2, s[20:21]
	v_readlane_b32 s20, v255, 7
	v_readlane_b32 s21, v255, 8
	v_mov_b32_e32 v21, 1.0
	s_andn2_b64 vcc, exec, s[20:21]
	v_cndmask_b32_e64 v23, 0, 1, s[20:21]
	v_cmp_ne_u32_e64 s[40:41], 1, v23
	v_mov_b32_e32 v23, 1.0
	s_cbranch_vccnz .LBB0_632
	flat_load_dword v23, v[2:3]

; DI void transpose_job(const int tid_, const float* __restrict__ src, const float* __restrict__ scale, u16* __restrict__ dst, u16* __restrict__ dst2,
;                       int K, int N, int kt, int nt, char* s0, char* s1, char* s2) {
;   float* tile = (float*)s0;
;   const int tid = tid_;
;   __syncthreads();
; #pragma unroll
;   for (int i = 0; i < 16; ++i) {
;     int kl = (tid >> 6) + 4 * i, nl = tid & 63;
;     int k = kt * 64 + kl, n = nt * 64 + nl;
;     tile[kl * 65 + nl] = (n < N) ? src[(size_t)k * N + n] : 0.f;
;   }
;   __syncthreads();
; DI void wprep_job(const int tid_, const Params& p, int l, int j, char* s0, char* s1, char* s2) {
;     ...
;     transpose_job(tid_, p.in[I_A2] + (size_t)l * 64 * 512, nullptr, (u16*)(p.ws + WS_A2) + (size_t)l * 512 * 64, nullptr, 64, 512, 0, j - 1384, s0, s1, s2);
.LBB0_699:
	s_andn2_b64 vcc, exec, s[2:3]
	s_cbranch_vccnz .LBB0_701
	s_lshl_b32 s2, s8, 6
	v_ashrrev_i32_e32 v18, 6, v35
	v_and_b32_e32 v40, 63, v34
	s_add_i32 s2, s2, 0xfffea600
	v_or_b32_e32 v0, s2, v40
	v_ashrrev_i32_e32 v19, 31, v18
	v_lshl_add_u64 v[36:37], v[0:1], 2, s[94:95]
	v_lshlrev_b64 v[2:3], 11, v[18:19]
	v_lshl_add_u64 v[2:3], v[36:37], 0, v[2:3]
	s_waitcnt lgkmcnt(0)
	s_barrier
	flat_load_dword v0, v[2:3]
	s_movk_i32 s3, 0x104
	v_add_u32_e32 v26, 4, v18
	v_mul_lo_u32 v2, v18, s3
	v_ashrrev_i32_e32 v27, 31, v26
	v_lshl_add_u32 v19, v40, 2, v2
	v_lshlrev_b64 v[2:3], 11, v[26:27]
	v_lshl_add_u64 v[2:3], v[36:37], 0, v[2:3]
	v_add_u32_e32 v28, 8, v18
	v_ashrrev_i32_e32 v29, 31, v28
	v_add_u32_e32 v30, 12, v18
	v_ashrrev_i32_e32 v31, 31, v30
	v_add_u32_e32 v32, 16, v18
	v_ashrrev_i32_e32 v33, 31, v32
	v_add_u32_e32 v22, 20, v18
	v_ashrrev_i32_e32 v23, 31, v22
	v_add_u32_e32 v24, 24, v18
	v_ashrrev_i32_e32 v25, 31, v24
	v_add_u32_e32 v8, 28, v18
	v_ashrrev_i32_e32 v9, 31, v8
	v_add_u32_e32 v20, 32, v18
	v_ashrrev_i32_e32 v21, 31, v20
	v_add_u32_e32 v4, 36, v18
	v_ashrrev_i32_e32 v5, 31, v4
	v_add_u32_e32 v6, 40, v18
	v_ashrrev_i32_e32 v7, 31, v6
	v_add_u32_e32 v10, 44, v18
	v_ashrrev_i32_e32 v11, 31, v10
	v_add_u32_e32 v12, 48, v18
	v_ashrrev_i32_e32 v13, 31, v12
	v_add_u32_e32 v14, 52, v18
	v_ashrrev_i32_e32 v15, 31, v14
	v_add_u32_e32 v16, 56, v18
	v_ashrrev_i32_e32 v17, 31, v16
	s_waitcnt vmcnt(0) lgkmcnt(0)
	ds_write_b32 v19, v0
	flat_load_dword v206, v[2:3]
	v_lshlrev_b64 v[2:3], 11, v[28:29]
	v_lshl_add_u64 v[2:3], v[36:37], 0, v[2:3]
	flat_load_dword v207, v[2:3]
	v_lshlrev_b64 v[2:3], 11, v[30:31]
	v_lshl_add_u64 v[2:3], v[36:37], 0, v[2:3]
	flat_load_dword v208, v[2:3]
	v_lshlrev_b64 v[2:3], 11, v[32:33]
	v_lshl_add_u64 v[2:3], v[36:37], 0, v[2:3]
	flat_load_dword v209, v[2:3]
	v_lshlrev_b64 v[2:3], 11, v[22:23]
	v_lshl_add_u64 v[2:3], v[36:37], 0, v[2:3]
	flat_load_dword v210, v[2:3]
	v_lshlrev_b64 v[2:3], 11, v[24:25]
	v_lshl_add_u64 v[2:3], v[36:37], 0, v[2:3]
	flat_load_dword v211, v[2:3]
	v_lshlrev_b64 v[2:3], 11, v[8:9]
	v_lshl_add_u64 v[2:3], v[36:37], 0, v[2:3]
	v_add_u32_e32 v8, s2, v8
	v_ashrrev_i32_e32 v9, 31, v8
	v_lshlrev_b64 v[8:9], 7, v[8:9]
	v_lshl_add_u64 v[8:9], s[84:85], 0, v[8:9]
	flat_load_dword v212, v[2:3]
	v_lshlrev_b64 v[2:3], 11, v[20:21]
	v_lshl_add_u64 v[2:3], v[36:37], 0, v[2:3]
	flat_load_dword v213, v[2:3]
	v_lshlrev_b64 v[2:3], 11, v[4:5]
	v_lshl_add_u64 v[2:3], v[36:37], 0, v[2:3]
	v_add_u32_e32 v4, s2, v4
	flat_load_dword v214, v[2:3]
	v_lshlrev_b64 v[2:3], 11, v[6:7]
	v_lshl_add_u64 v[2:3], v[36:37], 0, v[2:3]
	flat_load_dword v215, v[2:3]
	v_lshlrev_b64 v[2:3], 11, v[10:11]
	v_lshl_add_u64 v[2:3], v[36:37], 0, v[2:3]
	flat_load_dword v216, v[2:3]
	v_lshlrev_b64 v[2:3], 11, v[12:13]
	v_lshl_add_u64 v[2:3], v[36:37], 0, v[2:3]
	flat_load_dword v217, v[2:3]
	v_lshlrev_b64 v[2:3], 11, v[14:15]
	v_lshl_add_u64 v[2:3], v[36:37], 0, v[2:3]
	flat_load_dword v218, v[2:3]
	v_lshlrev_b64 v[2:3], 11, v[16:17]
	v_lshl_add_u64 v[2:3], v[36:37], 0, v[2:3]
	flat_load_dword v219, v[2:3]
	v_add_u32_e32 v2, 60, v18
	v_ashrrev_i32_e32 v3, 31, v2
	v_lshlrev_b64 v[38:39], 11, v[2:3]
	v_lshl_add_u64 v[36:37], v[36:37], 0, v[38:39]
	v_add_u32_e32 v2, s2, v2
	flat_load_dword v220, v[36:37]
	v_add_u32_e32 v36, s2, v18
	v_ashrrev_i32_e32 v37, 31, v36
	v_lshlrev_b64 v[36:37], 7, v[36:37]
	v_lshl_add_u64 v[36:37], s[84:85], 0, v[36:37]
	s_waitcnt vmcnt(14) lgkmcnt(0)
	ds_write_b32 v19, v206 offset:1040
	s_waitcnt vmcnt(13)
	ds_write_b32 v19, v207 offset:2080
	s_waitcnt vmcnt(12)
	ds_write_b32 v19, v208 offset:3120
	s_waitcnt vmcnt(11)
	ds_write_b32 v19, v209 offset:4160
	s_waitcnt vmcnt(10)
	ds_write_b32 v19, v210 offset:5200
	s_waitcnt vmcnt(9)
	ds_write_b32 v19, v211 offset:6240
	s_waitcnt vmcnt(8)
	ds_write_b32 v19, v212 offset:7280
	s_waitcnt vmcnt(7)
	ds_write_b32 v19, v213 offset:8320
	s_waitcnt vmcnt(6)
	ds_write_b32 v19, v214 offset:9360
	s_waitcnt vmcnt(5)
	ds_write_b32 v19, v215 offset:10400
	s_waitcnt vmcnt(4)
	ds_write_b32 v19, v216 offset:11440
	s_waitcnt vmcnt(3)
	ds_write_b32 v19, v217 offset:12480
	s_waitcnt vmcnt(2)
	ds_write_b32 v19, v218 offset:13520
	s_waitcnt vmcnt(1)
	ds_write_b32 v19, v219 offset:14560
	s_waitcnt vmcnt(0)
	ds_write_b32 v19, v220 offset:15600
	v_lshlrev_b32_e32 v0, 2, v18
	v_mad_u32_u24 v3, v40, s3, v0
	s_waitcnt lgkmcnt(0)
	s_barrier
; DI void transpose_job(const int tid_, const float* __restrict__ src, const float* __restrict__ scale, u16* __restrict__ dst, u16* __restrict__ dst2,
;                       int K, int N, int kt, int nt, char* s0, char* s1, char* s2) {
;     ...
; #pragma unroll
;   for (int i = 0; i < 16; ++i) {
;     int nl = (tid >> 6) + 4 * i, kl = tid & 63;
;     int k = kt * 64 + kl, n = nt * 64 + nl;
;     float v = tile[kl * 65 + nl];
;     float sc = scale ? scale[k] : 1.f;
;     dst[(size_t)n * K + k] = (u16)(pack2(v * sc, 0.f) & 0xffffu);
;     if (dst2) dst2[(size_t)n * K + k] = (u16)(pack2(v, 0.f) & 0xffffu);
;   }
	ds_read2_b32 v[18:19], v3 offset1:4
	ds_read2_b32 v[38:39], v3 offset0:8 offset1:12
	v_lshlrev_b32_e32 v0, 1, v40
	v_lshl_add_u64 v[36:37], v[36:37], 0, v[0:1]
	v_lshl_add_u64 v[8:9], v[8:9], 0, v[0:1]
	s_waitcnt lgkmcnt(1)
	v_cvt_pk_bf16_f32 v5, v18, s0
	v_add_u32_e32 v18, s2, v26
	flat_store_short v[36:37], v5
	v_cvt_pk_bf16_f32 v5, v19, s0
	v_ashrrev_i32_e32 v19, 31, v18
	v_lshlrev_b64 v[18:19], 7, v[18:19]
	v_lshl_add_u64 v[18:19], s[84:85], 0, v[18:19]
	v_lshl_add_u64 v[18:19], v[18:19], 0, v[0:1]
	flat_store_short v[18:19], v5
	v_add_u32_e32 v18, s2, v28
	v_ashrrev_i32_e32 v19, 31, v18
	v_lshlrev_b64 v[18:19], 7, v[18:19]
	v_lshl_add_u64 v[18:19], s[84:85], 0, v[18:19]
	s_waitcnt lgkmcnt(0)
	v_cvt_pk_bf16_f32 v5, v38, s0
	v_lshl_add_u64 v[18:19], v[18:19], 0, v[0:1]
	flat_store_short v[18:19], v5
	v_add_u32_e32 v18, s2, v30
	v_ashrrev_i32_e32 v19, 31, v18
	v_lshlrev_b64 v[18:19], 7, v[18:19]
	v_lshl_add_u64 v[18:19], s[84:85], 0, v[18:19]
	v_cvt_pk_bf16_f32 v5, v39, s0
	v_lshl_add_u64 v[18:19], v[18:19], 0, v[0:1]
	ds_read2_b32 v[26:27], v3 offset0:16 offset1:20
	flat_store_short v[18:19], v5
	v_add_u32_e32 v18, s2, v32
	v_ashrrev_i32_e32 v19, 31, v18
	v_lshlrev_b64 v[18:19], 7, v[18:19]
	v_lshl_add_u64 v[18:19], s[84:85], 0, v[18:19]
	s_waitcnt lgkmcnt(0)
	v_cvt_pk_bf16_f32 v5, v26, s0
	v_lshl_add_u64 v[18:19], v[18:19], 0, v[0:1]
	flat_store_short v[18:19], v5
	v_add_u32_e32 v18, s2, v22
	v_ashrrev_i32_e32 v19, 31, v18
	v_lshlrev_b64 v[18:19], 7, v[18:19]
	v_lshl_add_u64 v[18:19], s[84:85], 0, v[18:19]
	v_cvt_pk_bf16_f32 v5, v27, s0
	v_lshl_add_u64 v[18:19], v[18:19], 0, v[0:1]
	ds_read2_b32 v[22:23], v3 offset0:24 offset1:28
	flat_store_short v[18:19], v5
	v_add_u32_e32 v18, s2, v24
	v_ashrrev_i32_e32 v19, 31, v18
	v_lshlrev_b64 v[18:19], 7, v[18:19]
	v_lshl_add_u64 v[18:19], s[84:85], 0, v[18:19]
	s_waitcnt lgkmcnt(0)
	v_cvt_pk_bf16_f32 v5, v22, s0
	v_lshl_add_u64 v[18:19], v[18:19], 0, v[0:1]
	flat_store_short v[18:19], v5
	v_cvt_pk_bf16_f32 v5, v23, s0
	ds_read2_b32 v[18:19], v3 offset0:32 offset1:36
	flat_store_short v[8:9], v5
	v_add_u32_e32 v8, s2, v20
	v_ashrrev_i32_e32 v9, 31, v8
	v_lshlrev_b64 v[8:9], 7, v[8:9]
	v_lshl_add_u64 v[8:9], s[84:85], 0, v[8:9]
	s_waitcnt lgkmcnt(0)
	v_cvt_pk_bf16_f32 v5, v18, s0
	v_lshl_add_u64 v[8:9], v[8:9], 0, v[0:1]
	flat_store_short v[8:9], v5
	v_ashrrev_i32_e32 v5, 31, v4
	v_lshlrev_b64 v[4:5], 7, v[4:5]
	v_lshl_add_u64 v[4:5], s[84:85], 0, v[4:5]
	v_cvt_pk_bf16_f32 v7, v19, s0
	v_lshl_add_u64 v[4:5], v[4:5], 0, v[0:1]
	ds_read2_b32 v[8:9], v3 offset0:40 offset1:44
	ds_read2_b32 v[20:21], v3 offset0:48 offset1:52
	flat_store_short v[4:5], v7
	v_add_u32_e32 v4, s2, v6
	v_ashrrev_i32_e32 v5, 31, v4
	v_lshlrev_b64 v[4:5], 7, v[4:5]
	v_lshl_add_u64 v[4:5], s[84:85], 0, v[4:5]
	s_waitcnt lgkmcnt(0)
	v_cvt_pk_bf16_f32 v6, v8, s0
	v_lshl_add_u64 v[4:5], v[4:5], 0, v[0:1]
	flat_store_short v[4:5], v6
	v_add_u32_e32 v4, s2, v10
	v_ashrrev_i32_e32 v5, 31, v4
	v_lshlrev_b64 v[4:5], 7, v[4:5]
	v_lshl_add_u64 v[4:5], s[84:85], 0, v[4:5]
	v_cvt_pk_bf16_f32 v6, v9, s0
	v_lshl_add_u64 v[4:5], v[4:5], 0, v[0:1]
	flat_store_short v[4:5], v6
	v_add_u32_e32 v4, s2, v12
	v_ashrrev_i32_e32 v5, 31, v4
	v_lshlrev_b64 v[4:5], 7, v[4:5]
	v_lshl_add_u64 v[4:5], s[84:85], 0, v[4:5]
	v_cvt_pk_bf16_f32 v6, v20, s0
	v_lshl_add_u64 v[4:5], v[4:5], 0, v[0:1]
	flat_store_short v[4:5], v6
	v_add_u32_e32 v4, s2, v14
	v_ashrrev_i32_e32 v5, 31, v4
	v_lshlrev_b64 v[4:5], 7, v[4:5]
	v_lshl_add_u64 v[4:5], s[84:85], 0, v[4:5]
	v_cvt_pk_bf16_f32 v6, v21, s0
	v_lshl_add_u64 v[4:5], v[4:5], 0, v[0:1]
	flat_store_short v[4:5], v6
	ds_read2_b32 v[6:7], v3 offset0:56 offset1:60
	v_add_u32_e32 v4, s2, v16
	v_ashrrev_i32_e32 v5, 31, v4
	v_lshlrev_b64 v[4:5], 7, v[4:5]
	v_lshl_add_u64 v[4:5], s[84:85], 0, v[4:5]
	s_waitcnt lgkmcnt(0)
	v_cvt_pk_bf16_f32 v3, v6, s0
	v_lshl_add_u64 v[4:5], v[4:5], 0, v[0:1]
	flat_store_short v[4:5], v3
	v_ashrrev_i32_e32 v3, 31, v2
	v_lshlrev_b64 v[2:3], 7, v[2:3]
	v_lshl_add_u64 v[2:3], s[84:85], 0, v[2:3]
	v_cvt_pk_bf16_f32 v4, v7, s0
	v_lshl_add_u64 v[2:3], v[2:3], 0, v[0:1]
	flat_store_short v[2:3], v4

; DI void transpose_job(const int tid_, const float* __restrict__ src, const float* __restrict__ scale, u16* __restrict__ dst, u16* __restrict__ dst2,
;                       int K, int N, int kt, int nt, char* s0, char* s1, char* s2) {
;   float* tile = (float*)s0;
;   const int tid = tid_;
;   __syncthreads();
; #pragma unroll
;   for (int i = 0; i < 16; ++i) {
;     int kl = (tid >> 6) + 4 * i, nl = tid & 63;
;     int k = kt * 64 + kl, n = nt * 64 + nl;
;     tile[kl * 65 + nl] = (n < N) ? src[(size_t)k * N + n] : 0.f;
;   }
;   __syncthreads();
; DI void wprep_job(const int tid_, const Params& p, int l, int j, char* s0, char* s1, char* s2) {
;     ...
;     transpose_job(tid_, p.in[I_W2] + (size_t)l * 64 * 512, nullptr, (u16*)(p.ws + WS_W2) + (size_t)l * 512 * 64, nullptr, 64, 512, 0, j - 1376, s0, s1, s2);
.LBB0_702:
	s_andn2_b64 vcc, exec, s[2:3]
	s_cbranch_vccnz .LBB0_704
	s_lshl_b32 s2, s8, 6
	v_ashrrev_i32_e32 v18, 6, v35
	v_and_b32_e32 v40, 63, v34
	s_add_i32 s2, s2, 0xfffea800
	v_or_b32_e32 v0, s2, v40
	v_ashrrev_i32_e32 v19, 31, v18
	v_lshl_add_u64 v[36:37], v[0:1], 2, s[92:93]
	v_lshlrev_b64 v[2:3], 11, v[18:19]
	v_lshl_add_u64 v[2:3], v[36:37], 0, v[2:3]
	s_waitcnt lgkmcnt(0)
	s_barrier
	flat_load_dword v0, v[2:3]
	s_movk_i32 s3, 0x104
	v_add_u32_e32 v26, 4, v18
	v_mul_lo_u32 v2, v18, s3
	v_ashrrev_i32_e32 v27, 31, v26
	v_lshl_add_u32 v19, v40, 2, v2
	v_lshlrev_b64 v[2:3], 11, v[26:27]
	v_lshl_add_u64 v[2:3], v[36:37], 0, v[2:3]
	v_add_u32_e32 v28, 8, v18
	v_ashrrev_i32_e32 v29, 31, v28
	v_add_u32_e32 v30, 12, v18
	v_ashrrev_i32_e32 v31, 31, v30
	v_add_u32_e32 v32, 16, v18
	v_ashrrev_i32_e32 v33, 31, v32
	v_add_u32_e32 v22, 20, v18
	v_ashrrev_i32_e32 v23, 31, v22
	v_add_u32_e32 v24, 24, v18
	v_ashrrev_i32_e32 v25, 31, v24
	v_add_u32_e32 v8, 28, v18
	v_ashrrev_i32_e32 v9, 31, v8
	v_add_u32_e32 v20, 32, v18
	v_ashrrev_i32_e32 v21, 31, v20
	v_add_u32_e32 v4, 36, v18
	v_ashrrev_i32_e32 v5, 31, v4
	v_add_u32_e32 v6, 40, v18
	v_ashrrev_i32_e32 v7, 31, v6
	v_add_u32_e32 v10, 44, v18
	v_ashrrev_i32_e32 v11, 31, v10
	v_add_u32_e32 v12, 48, v18
	v_ashrrev_i32_e32 v13, 31, v12
	v_add_u32_e32 v14, 52, v18
	v_ashrrev_i32_e32 v15, 31, v14
	v_add_u32_e32 v16, 56, v18
	v_ashrrev_i32_e32 v17, 31, v16
	s_waitcnt vmcnt(0) lgkmcnt(0)
	ds_write_b32 v19, v0
	flat_load_dword v206, v[2:3]
	v_lshlrev_b64 v[2:3], 11, v[28:29]
	v_lshl_add_u64 v[2:3], v[36:37], 0, v[2:3]
	flat_load_dword v207, v[2:3]
	v_lshlrev_b64 v[2:3], 11, v[30:31]
	v_lshl_add_u64 v[2:3], v[36:37], 0, v[2:3]
	flat_load_dword v208, v[2:3]
	v_lshlrev_b64 v[2:3], 11, v[32:33]
	v_lshl_add_u64 v[2:3], v[36:37], 0, v[2:3]
	flat_load_dword v209, v[2:3]
	v_lshlrev_b64 v[2:3], 11, v[22:23]
	v_lshl_add_u64 v[2:3], v[36:37], 0, v[2:3]
	flat_load_dword v210, v[2:3]
	v_lshlrev_b64 v[2:3], 11, v[24:25]
	v_lshl_add_u64 v[2:3], v[36:37], 0, v[2:3]
	flat_load_dword v211, v[2:3]
	v_lshlrev_b64 v[2:3], 11, v[8:9]
	v_lshl_add_u64 v[2:3], v[36:37], 0, v[2:3]
	v_add_u32_e32 v8, s2, v8
	v_ashrrev_i32_e32 v9, 31, v8
	v_lshlrev_b64 v[8:9], 7, v[8:9]
	v_lshl_add_u64 v[8:9], s[10:11], 0, v[8:9]
	flat_load_dword v212, v[2:3]
	v_lshlrev_b64 v[2:3], 11, v[20:21]
	v_lshl_add_u64 v[2:3], v[36:37], 0, v[2:3]
	flat_load_dword v213, v[2:3]
	v_lshlrev_b64 v[2:3], 11, v[4:5]
	v_lshl_add_u64 v[2:3], v[36:37], 0, v[2:3]
	v_add_u32_e32 v4, s2, v4
	flat_load_dword v214, v[2:3]
	v_lshlrev_b64 v[2:3], 11, v[6:7]
	v_lshl_add_u64 v[2:3], v[36:37], 0, v[2:3]
	flat_load_dword v215, v[2:3]
	v_lshlrev_b64 v[2:3], 11, v[10:11]
	v_lshl_add_u64 v[2:3], v[36:37], 0, v[2:3]
	flat_load_dword v216, v[2:3]
	v_lshlrev_b64 v[2:3], 11, v[12:13]
	v_lshl_add_u64 v[2:3], v[36:37], 0, v[2:3]
	flat_load_dword v217, v[2:3]
	v_lshlrev_b64 v[2:3], 11, v[14:15]
	v_lshl_add_u64 v[2:3], v[36:37], 0, v[2:3]
	flat_load_dword v218, v[2:3]
	v_lshlrev_b64 v[2:3], 11, v[16:17]
	v_lshl_add_u64 v[2:3], v[36:37], 0, v[2:3]
	flat_load_dword v219, v[2:3]
	v_add_u32_e32 v2, 60, v18
	v_ashrrev_i32_e32 v3, 31, v2
	v_lshlrev_b64 v[38:39], 11, v[2:3]
	v_lshl_add_u64 v[36:37], v[36:37], 0, v[38:39]
	v_add_u32_e32 v2, s2, v2
	flat_load_dword v220, v[36:37]
	v_add_u32_e32 v36, s2, v18
	v_ashrrev_i32_e32 v37, 31, v36
	v_lshlrev_b64 v[36:37], 7, v[36:37]
	v_lshl_add_u64 v[36:37], s[10:11], 0, v[36:37]
	s_waitcnt vmcnt(14) lgkmcnt(0)
	ds_write_b32 v19, v206 offset:1040
	s_waitcnt vmcnt(13)
	ds_write_b32 v19, v207 offset:2080
	s_waitcnt vmcnt(12)
	ds_write_b32 v19, v208 offset:3120
	s_waitcnt vmcnt(11)
	ds_write_b32 v19, v209 offset:4160
	s_waitcnt vmcnt(10)
	ds_write_b32 v19, v210 offset:5200
	s_waitcnt vmcnt(9)
	ds_write_b32 v19, v211 offset:6240
	s_waitcnt vmcnt(8)
	ds_write_b32 v19, v212 offset:7280
	s_waitcnt vmcnt(7)
	ds_write_b32 v19, v213 offset:8320
	s_waitcnt vmcnt(6)
	ds_write_b32 v19, v214 offset:9360
	s_waitcnt vmcnt(5)
	ds_write_b32 v19, v215 offset:10400
	s_waitcnt vmcnt(4)
	ds_write_b32 v19, v216 offset:11440
	s_waitcnt vmcnt(3)
	ds_write_b32 v19, v217 offset:12480
	s_waitcnt vmcnt(2)
	ds_write_b32 v19, v218 offset:13520
	s_waitcnt vmcnt(1)
	ds_write_b32 v19, v219 offset:14560
	s_waitcnt vmcnt(0)
	ds_write_b32 v19, v220 offset:15600
	v_lshlrev_b32_e32 v0, 2, v18
	v_mad_u32_u24 v3, v40, s3, v0
	s_waitcnt lgkmcnt(0)
	s_barrier
; DI void transpose_job(const int tid_, const float* __restrict__ src, const float* __restrict__ scale, u16* __restrict__ dst, u16* __restrict__ dst2,
;                       int K, int N, int kt, int nt, char* s0, char* s1, char* s2) {
;     ...
; #pragma unroll
;   for (int i = 0; i < 16; ++i) {
;     int nl = (tid >> 6) + 4 * i, kl = tid & 63;
;     int k = kt * 64 + kl, n = nt * 64 + nl;
;     float v = tile[kl * 65 + nl];
;     float sc = scale ? scale[k] : 1.f;
;     dst[(size_t)n * K + k] = (u16)(pack2(v * sc, 0.f) & 0xffffu);
;     if (dst2) dst2[(size_t)n * K + k] = (u16)(pack2(v, 0.f) & 0xffffu);
;   }
	ds_read2_b32 v[18:19], v3 offset1:4
	ds_read2_b32 v[38:39], v3 offset0:8 offset1:12
	v_lshlrev_b32_e32 v0, 1, v40
	v_lshl_add_u64 v[36:37], v[36:37], 0, v[0:1]
	v_lshl_add_u64 v[8:9], v[8:9], 0, v[0:1]
	s_waitcnt lgkmcnt(1)
	v_cvt_pk_bf16_f32 v5, v18, s0
	v_add_u32_e32 v18, s2, v26
	flat_store_short v[36:37], v5
	v_cvt_pk_bf16_f32 v5, v19, s0
	v_ashrrev_i32_e32 v19, 31, v18
	v_lshlrev_b64 v[18:19], 7, v[18:19]
	v_lshl_add_u64 v[18:19], s[10:11], 0, v[18:19]
	v_lshl_add_u64 v[18:19], v[18:19], 0, v[0:1]
	flat_store_short v[18:19], v5
	v_add_u32_e32 v18, s2, v28
	v_ashrrev_i32_e32 v19, 31, v18
	v_lshlrev_b64 v[18:19], 7, v[18:19]
	v_lshl_add_u64 v[18:19], s[10:11], 0, v[18:19]
	s_waitcnt lgkmcnt(0)
	v_cvt_pk_bf16_f32 v5, v38, s0
	v_lshl_add_u64 v[18:19], v[18:19], 0, v[0:1]
	flat_store_short v[18:19], v5
	v_add_u32_e32 v18, s2, v30
	v_ashrrev_i32_e32 v19, 31, v18
	v_lshlrev_b64 v[18:19], 7, v[18:19]
	v_lshl_add_u64 v[18:19], s[10:11], 0, v[18:19]
	v_cvt_pk_bf16_f32 v5, v39, s0
	v_lshl_add_u64 v[18:19], v[18:19], 0, v[0:1]
	ds_read2_b32 v[26:27], v3 offset0:16 offset1:20
	flat_store_short v[18:19], v5
	v_add_u32_e32 v18, s2, v32
	v_ashrrev_i32_e32 v19, 31, v18
	v_lshlrev_b64 v[18:19], 7, v[18:19]
	v_lshl_add_u64 v[18:19], s[10:11], 0, v[18:19]
	s_waitcnt lgkmcnt(0)
	v_cvt_pk_bf16_f32 v5, v26, s0
	v_lshl_add_u64 v[18:19], v[18:19], 0, v[0:1]
	flat_store_short v[18:19], v5
	v_add_u32_e32 v18, s2, v22
	v_ashrrev_i32_e32 v19, 31, v18
	v_lshlrev_b64 v[18:19], 7, v[18:19]
	v_lshl_add_u64 v[18:19], s[10:11], 0, v[18:19]
	v_cvt_pk_bf16_f32 v5, v27, s0
	v_lshl_add_u64 v[18:19], v[18:19], 0, v[0:1]
	ds_read2_b32 v[22:23], v3 offset0:24 offset1:28
	flat_store_short v[18:19], v5
	v_add_u32_e32 v18, s2, v24
	v_ashrrev_i32_e32 v19, 31, v18
	v_lshlrev_b64 v[18:19], 7, v[18:19]
	v_lshl_add_u64 v[18:19], s[10:11], 0, v[18:19]
	s_waitcnt lgkmcnt(0)
	v_cvt_pk_bf16_f32 v5, v22, s0
	v_lshl_add_u64 v[18:19], v[18:19], 0, v[0:1]
	flat_store_short v[18:19], v5
	v_cvt_pk_bf16_f32 v5, v23, s0
	ds_read2_b32 v[18:19], v3 offset0:32 offset1:36
	flat_store_short v[8:9], v5
	v_add_u32_e32 v8, s2, v20
	v_ashrrev_i32_e32 v9, 31, v8
	v_lshlrev_b64 v[8:9], 7, v[8:9]
	v_lshl_add_u64 v[8:9], s[10:11], 0, v[8:9]
	s_waitcnt lgkmcnt(0)
	v_cvt_pk_bf16_f32 v5, v18, s0
	v_lshl_add_u64 v[8:9], v[8:9], 0, v[0:1]
	flat_store_short v[8:9], v5
	v_ashrrev_i32_e32 v5, 31, v4
	v_lshlrev_b64 v[4:5], 7, v[4:5]
	v_lshl_add_u64 v[4:5], s[10:11], 0, v[4:5]
	v_cvt_pk_bf16_f32 v7, v19, s0
	v_lshl_add_u64 v[4:5], v[4:5], 0, v[0:1]
	ds_read2_b32 v[8:9], v3 offset0:40 offset1:44
	ds_read2_b32 v[20:21], v3 offset0:48 offset1:52
	flat_store_short v[4:5], v7
	v_add_u32_e32 v4, s2, v6
	v_ashrrev_i32_e32 v5, 31, v4
	v_lshlrev_b64 v[4:5], 7, v[4:5]
	v_lshl_add_u64 v[4:5], s[10:11], 0, v[4:5]
	s_waitcnt lgkmcnt(0)
	v_cvt_pk_bf16_f32 v6, v8, s0
	v_lshl_add_u64 v[4:5], v[4:5], 0, v[0:1]
	flat_store_short v[4:5], v6
	v_add_u32_e32 v4, s2, v10
	v_ashrrev_i32_e32 v5, 31, v4
	v_lshlrev_b64 v[4:5], 7, v[4:5]
	v_lshl_add_u64 v[4:5], s[10:11], 0, v[4:5]
	v_cvt_pk_bf16_f32 v6, v9, s0
	v_lshl_add_u64 v[4:5], v[4:5], 0, v[0:1]
	flat_store_short v[4:5], v6
	v_add_u32_e32 v4, s2, v12
	v_ashrrev_i32_e32 v5, 31, v4
	v_lshlrev_b64 v[4:5], 7, v[4:5]
	v_lshl_add_u64 v[4:5], s[10:11], 0, v[4:5]
	v_cvt_pk_bf16_f32 v6, v20, s0
	v_lshl_add_u64 v[4:5], v[4:5], 0, v[0:1]
	flat_store_short v[4:5], v6
	v_add_u32_e32 v4, s2, v14
	v_ashrrev_i32_e32 v5, 31, v4
	v_lshlrev_b64 v[4:5], 7, v[4:5]
	v_lshl_add_u64 v[4:5], s[10:11], 0, v[4:5]
	v_cvt_pk_bf16_f32 v6, v21, s0
	v_lshl_add_u64 v[4:5], v[4:5], 0, v[0:1]
	flat_store_short v[4:5], v6
	ds_read2_b32 v[6:7], v3 offset0:56 offset1:60
	v_add_u32_e32 v4, s2, v16
	v_ashrrev_i32_e32 v5, 31, v4
	v_lshlrev_b64 v[4:5], 7, v[4:5]
	v_lshl_add_u64 v[4:5], s[10:11], 0, v[4:5]
	s_waitcnt lgkmcnt(0)
	v_cvt_pk_bf16_f32 v3, v6, s0
	v_lshl_add_u64 v[4:5], v[4:5], 0, v[0:1]
	flat_store_short v[4:5], v3
	v_ashrrev_i32_e32 v3, 31, v2
	v_lshlrev_b64 v[2:3], 7, v[2:3]
	v_lshl_add_u64 v[2:3], s[10:11], 0, v[2:3]
	v_cvt_pk_bf16_f32 v4, v7, s0
	v_lshl_add_u64 v[2:3], v[2:3], 0, v[0:1]
	flat_store_short v[2:3], v4

; DI void transpose_job(const int tid_, const float* __restrict__ src, const float* __restrict__ scale, u16* __restrict__ dst, u16* __restrict__ dst2,
;                       int K, int N, int kt, int nt, char* s0, char* s1, char* s2) {
;     ...
;   __syncthreads();
; #pragma unroll
;   for (int i = 0; i < 16; ++i) {
;     int kl = (tid >> 6) + 4 * i, nl = tid & 63;
;     int k = kt * 64 + kl, n = nt * 64 + nl;
;     tile[kl * 65 + nl] = (n < N) ? src[(size_t)k * N + n] : 0.f;
;   }
;   __syncthreads();
; DI void wprep_job(const int tid_, const Params& p, int l, int j, char* s0, char* s1, char* s2) {
;   if (j < 1376) {
;     transpose_job(tid_, p.in[I_WIN] + (size_t)l * 1024 * ZC, p.in[I_NORMW] + l * 1024, (u16*)(p.ws + WS_WIN) + (size_t)l * 5504 * 1024, nullptr,
;                   1024, ZC, j / 86, j % 86, s0, s1, s2);
;   } else if (j < 1384) {
;     transpose_job(tid_, p.in[I_W2] + (size_t)l * 64 * 512, nullptr, (u16*)(p.ws + WS_W2) + (size_t)l * 512 * 64, nullptr, 64, 512, 0, j - 1376, s0, s1, s2);
;   } else if (j < 1392) {
;     transpose_job(tid_, p.in[I_A2] + (size_t)l * 64 * 512, nullptr, (u16*)(p.ws + WS_A2) + (size_t)l * 512 * 64, nullptr, 64, 512, 0, j - 1384, s0, s1, s2);
;   } else if (j < 1464) {
;     int q = j - 1392;
;     transpose_job(tid_, p.in[I_WUQ] + (size_t)l * 384 * 768, p.in[I_QNORM] + l * 384, (u16*)(p.ws + WS_WUQ) + (size_t)l * 768 * 384, nullptr,
;                   384, 768, q / 12, q % 12, s0, s1, s2);
;   } else if (j < 1528) {
;     int q = j - 1464;
;     transpose_job(tid_, p.in[I_WUKV] + (size_t)l * 256 * 1024, p.in[I_KVNORM] + l * 256, (u16*)(p.ws + WS_WKVF) + (size_t)l * 1024 * 256,
;                   (u16*)(p.ws + WS_WKVP) + (size_t)l * 1024 * 256, 256, 1024, q / 16, q % 16, s0, s1, s2);
;   } else if (j < 1656) {
;     int q = j - 1528;
;     transpose_job(tid_, p.in[I_WA] + (size_t)l * 512 * 1024, nullptr, (u16*)(p.ws + WS_WA) + (size_t)l * 1024 * 512, nullptr, 512, 1024, q / 16, q % 16, s0, s1, s2);
;   } else if (j < 1784) {
;     int q = j - 1656;
;     transpose_job(tid_, p.in[I_WB] + (size_t)l * 512 * 1024, nullptr, (u16*)(p.ws + WS_WB) + (size_t)l * 1024 * 512, nullptr, 512, 1024, q / 16, q % 16, s0, s1, s2);
;   } else {
;     int q = j - 1784;
.LBB0_992:
	s_cmpk_gt_i32 s8, 0x55f
	s_mov_b64 s[2:3], -1
	s_cbranch_scc0 .LBB0_1082
	s_cmpk_gt_u32 s8, 0x567
	s_cbranch_scc0 .LBB0_1079
	s_cmpk_gt_u32 s8, 0x56f
	s_cbranch_scc0 .LBB0_1076
	s_cmpk_gt_u32 s8, 0x5b7
	s_cbranch_scc0 .LBB0_1041
	s_cmpk_gt_u32 s8, 0x5f7
	s_cbranch_scc0 .LBB0_1006
	s_cmpk_gt_u32 s8, 0x677
	s_cbranch_scc0 .LBB0_1003
	s_cmpk_gt_u32 s8, 0x6f7
	s_cbranch_scc0 .LBB0_1000
	s_and_b32 s2, s9, 0x3c0
	s_and_b32 s3, s20, 0x7fffffc0
	v_or_b32_e32 v0, s2, v74
	v_add_u32_e32 v72, s3, v2
	v_lshlrev_b32_e32 v0, 2, v0
	v_ashrrev_i32_e32 v73, 31, v72
	v_lshl_add_u64 v[70:71], s[62:63], 0, v[0:1]
	v_lshlrev_b64 v[72:73], 12, v[72:73]
	v_lshl_add_u64 v[72:73], v[70:71], 0, v[72:73]
	s_waitcnt lgkmcnt(0)
	s_barrier
	flat_load_dword v206, v[72:73]
	v_add_u32_e32 v72, s3, v4
	v_ashrrev_i32_e32 v73, 31, v72
	v_lshlrev_b64 v[72:73], 12, v[72:73]
	v_add_u32_e32 v5, v75, v76
	v_lshl_add_u64 v[72:73], v[70:71], 0, v[72:73]
	flat_load_dword v207, v[72:73]
	v_add_u32_e32 v72, s3, v6
	v_ashrrev_i32_e32 v73, 31, v72
	v_lshlrev_b64 v[72:73], 12, v[72:73]
	v_lshl_add_u64 v[72:73], v[70:71], 0, v[72:73]
	flat_load_dword v208, v[72:73]
	v_add_u32_e32 v72, s3, v8
	v_ashrrev_i32_e32 v73, 31, v72
	v_lshlrev_b64 v[72:73], 12, v[72:73]
	v_lshl_add_u64 v[72:73], v[70:71], 0, v[72:73]
	flat_load_dword v209, v[72:73]
	v_add_u32_e32 v72, s3, v10
	v_ashrrev_i32_e32 v73, 31, v72
	v_lshlrev_b64 v[72:73], 12, v[72:73]
	v_lshl_add_u64 v[72:73], v[70:71], 0, v[72:73]
	flat_load_dword v210, v[72:73]
	v_add_u32_e32 v72, s3, v12
	v_ashrrev_i32_e32 v73, 31, v72
	v_lshlrev_b64 v[72:73], 12, v[72:73]
	v_lshl_add_u64 v[72:73], v[70:71], 0, v[72:73]
	flat_load_dword v211, v[72:73]
	v_add_u32_e32 v72, s3, v14
	v_ashrrev_i32_e32 v73, 31, v72
	v_lshlrev_b64 v[72:73], 12, v[72:73]
	v_lshl_add_u64 v[72:73], v[70:71], 0, v[72:73]
	s_waitcnt vmcnt(5) lgkmcnt(0)
	ds_write_b32 v5, v206
	s_waitcnt vmcnt(4)
	ds_write_b32 v5, v207 offset:1040
	s_waitcnt vmcnt(3)
	ds_write_b32 v5, v208 offset:2080
	s_waitcnt vmcnt(2)
	ds_write_b32 v5, v209 offset:3120
	s_waitcnt vmcnt(1)
	ds_write_b32 v5, v210 offset:4160
	s_waitcnt vmcnt(0)
	ds_write_b32 v5, v211 offset:5200
	flat_load_dword v206, v[72:73]
	v_add_u32_e32 v72, s3, v16
	v_ashrrev_i32_e32 v73, 31, v72
	v_lshlrev_b64 v[72:73], 12, v[72:73]
	v_add_u32_e32 v5, v75, v77
	v_lshl_add_u64 v[72:73], v[70:71], 0, v[72:73]
	flat_load_dword v207, v[72:73]
	v_add_u32_e32 v72, s3, v18
	v_ashrrev_i32_e32 v73, 31, v72
	v_lshlrev_b64 v[72:73], 12, v[72:73]
	v_lshl_add_u64 v[72:73], v[70:71], 0, v[72:73]
	flat_load_dword v208, v[72:73]
	v_add_u32_e32 v72, s3, v20
	v_ashrrev_i32_e32 v73, 31, v72
	v_lshlrev_b64 v[72:73], 12, v[72:73]
	v_lshl_add_u64 v[72:73], v[70:71], 0, v[72:73]
	flat_load_dword v209, v[72:73]
	v_add_u32_e32 v72, s3, v22
	v_ashrrev_i32_e32 v73, 31, v72
	v_lshlrev_b64 v[72:73], 12, v[72:73]
	v_lshl_add_u64 v[72:73], v[70:71], 0, v[72:73]
	flat_load_dword v210, v[72:73]
	v_add_u32_e32 v72, s3, v24
	v_ashrrev_i32_e32 v73, 31, v72
	v_lshlrev_b64 v[72:73], 12, v[72:73]
	v_lshl_add_u64 v[72:73], v[70:71], 0, v[72:73]
	flat_load_dword v211, v[72:73]
	v_add_u32_e32 v72, s3, v26
	v_ashrrev_i32_e32 v73, 31, v72
	v_lshlrev_b64 v[72:73], 12, v[72:73]
	v_lshl_add_u64 v[72:73], v[70:71], 0, v[72:73]
	flat_load_dword v212, v[72:73]
	v_add_u32_e32 v72, s3, v28
	v_ashrrev_i32_e32 v73, 31, v72
	v_lshlrev_b64 v[72:73], 12, v[72:73]
	v_lshl_add_u64 v[72:73], v[70:71], 0, v[72:73]
	flat_load_dword v213, v[72:73]
	v_add_u32_e32 v72, s3, v30
	v_ashrrev_i32_e32 v73, 31, v72
	v_lshlrev_b64 v[72:73], 12, v[72:73]
	v_lshl_add_u64 v[72:73], v[70:71], 0, v[72:73]
	flat_load_dword v214, v[72:73]
	v_add_u32_e32 v72, s3, v32
	v_ashrrev_i32_e32 v73, 31, v72
	v_lshlrev_b64 v[72:73], 12, v[72:73]
	v_lshl_add_u64 v[70:71], v[70:71], 0, v[72:73]
	flat_load_dword v215, v[70:71]
	v_add_u32_e32 v70, s2, v2
	v_ashrrev_i32_e32 v71, 31, v70
	v_lshlrev_b64 v[70:71], 11, v[70:71]
	v_lshl_add_u64 v[70:71], s[40:41], 0, v[70:71]
	s_waitcnt vmcnt(9) lgkmcnt(0)
	ds_write_b32 v5, v206
	s_waitcnt vmcnt(8)
	ds_write_b32 v5, v207 offset:1040
	s_waitcnt vmcnt(7)
	ds_write_b32 v5, v208 offset:2080
	s_waitcnt vmcnt(6)
	ds_write_b32 v5, v209 offset:3120
	s_waitcnt vmcnt(5)
	ds_write_b32 v5, v210 offset:4160
	s_waitcnt vmcnt(4)
	ds_write_b32 v5, v211 offset:5200
	s_waitcnt vmcnt(3)
	ds_write_b32 v5, v212 offset:6240
	s_waitcnt vmcnt(2)
	ds_write_b32 v5, v213 offset:7280
	s_waitcnt vmcnt(1)
	ds_write_b32 v5, v214 offset:8320
	s_waitcnt vmcnt(0)
	ds_write_b32 v5, v215 offset:9360
	s_waitcnt lgkmcnt(0)
	s_barrier
; DI void transpose_job(const int tid_, const float* __restrict__ src, const float* __restrict__ scale, u16* __restrict__ dst, u16* __restrict__ dst2,
;                       int K, int N, int kt, int nt, char* s0, char* s1, char* s2) {
;     ...
;   for (int i = 0; i < 16; ++i) {
;     int nl = (tid >> 6) + 4 * i, kl = tid & 63;
;     int k = kt * 64 + kl, n = nt * 64 + nl;
;     float v = tile[kl * 65 + nl];
;     float sc = scale ? scale[k] : 1.f;
;     dst[(size_t)n * K + k] = (u16)(pack2(v * sc, 0.f) & 0xffffu);
;     if (dst2) dst2[(size_t)n * K + k] = (u16)(pack2(v, 0.f) & 0xffffu);
;   }
	ds_read2_b32 v[72:73], v78 offset1:4
	ds_read2_b32 v[80:81], v78 offset0:8 offset1:12
	v_or_b32_e32 v0, s3, v74
	v_lshlrev_b32_e32 v0, 1, v0
	v_lshl_add_u64 v[70:71], v[70:71], 0, v[0:1]
	s_waitcnt lgkmcnt(1)
	v_cvt_pk_bf16_f32 v5, v72, s0
	flat_store_short v[70:71], v5
	v_add_u32_e32 v70, s2, v4
	v_ashrrev_i32_e32 v71, 31, v70
	v_lshlrev_b64 v[70:71], 11, v[70:71]
	v_lshl_add_u64 v[70:71], s[40:41], 0, v[70:71]
	v_cvt_pk_bf16_f32 v5, v73, s0
	v_lshl_add_u64 v[70:71], v[70:71], 0, v[0:1]
	flat_store_short v[70:71], v5
	v_add_u32_e32 v70, s2, v6
	v_ashrrev_i32_e32 v71, 31, v70
	v_lshlrev_b64 v[70:71], 11, v[70:71]
	v_lshl_add_u64 v[70:71], s[40:41], 0, v[70:71]
	s_waitcnt lgkmcnt(0)
	v_cvt_pk_bf16_f32 v5, v80, s0
	v_lshl_add_u64 v[70:71], v[70:71], 0, v[0:1]
	flat_store_short v[70:71], v5
	v_add_u32_e32 v70, s2, v8
	v_ashrrev_i32_e32 v71, 31, v70
	v_lshlrev_b64 v[70:71], 11, v[70:71]
	v_lshl_add_u64 v[70:71], s[40:41], 0, v[70:71]
	v_cvt_pk_bf16_f32 v5, v81, s0
	v_lshl_add_u64 v[70:71], v[70:71], 0, v[0:1]
	ds_read2_b32 v[72:73], v78 offset0:16 offset1:20
	flat_store_short v[70:71], v5
	v_add_u32_e32 v70, s2, v10
	v_ashrrev_i32_e32 v71, 31, v70
	v_lshlrev_b64 v[70:71], 11, v[70:71]
	v_lshl_add_u64 v[70:71], s[40:41], 0, v[70:71]
	s_waitcnt lgkmcnt(0)
	v_cvt_pk_bf16_f32 v5, v72, s0
	v_lshl_add_u64 v[70:71], v[70:71], 0, v[0:1]
	flat_store_short v[70:71], v5
	v_add_u32_e32 v70, s2, v12
	v_ashrrev_i32_e32 v71, 31, v70
	v_lshlrev_b64 v[70:71], 11, v[70:71]
	v_lshl_add_u64 v[70:71], s[40:41], 0, v[70:71]
	v_cvt_pk_bf16_f32 v5, v73, s0
	v_lshl_add_u64 v[70:71], v[70:71], 0, v[0:1]
	ds_read2_b32 v[72:73], v78 offset0:24 offset1:28
	flat_store_short v[70:71], v5
	v_add_u32_e32 v70, s2, v14
	v_ashrrev_i32_e32 v71, 31, v70
	v_lshlrev_b64 v[70:71], 11, v[70:71]
	v_lshl_add_u64 v[70:71], s[40:41], 0, v[70:71]
	s_waitcnt lgkmcnt(0)
	v_cvt_pk_bf16_f32 v5, v72, s0
	v_lshl_add_u64 v[70:71], v[70:71], 0, v[0:1]
	flat_store_short v[70:71], v5
	v_add_u32_e32 v70, s2, v16
	v_ashrrev_i32_e32 v71, 31, v70
	v_lshlrev_b64 v[70:71], 11, v[70:71]
	v_lshl_add_u64 v[70:71], s[40:41], 0, v[70:71]
	v_cvt_pk_bf16_f32 v5, v73, s0
	v_lshl_add_u64 v[70:71], v[70:71], 0, v[0:1]
	ds_read2_b32 v[72:73], v78 offset0:32 offset1:36
	flat_store_short v[70:71], v5
	v_add_u32_e32 v70, s2, v18
	v_ashrrev_i32_e32 v71, 31, v70
	v_lshlrev_b64 v[70:71], 11, v[70:71]
	v_lshl_add_u64 v[70:71], s[40:41], 0, v[70:71]
	s_waitcnt lgkmcnt(0)
	v_cvt_pk_bf16_f32 v5, v72, s0
	v_lshl_add_u64 v[70:71], v[70:71], 0, v[0:1]
	flat_store_short v[70:71], v5
	v_add_u32_e32 v70, s2, v20
	v_ashrrev_i32_e32 v71, 31, v70
	v_lshlrev_b64 v[70:71], 11, v[70:71]
	v_lshl_add_u64 v[70:71], s[40:41], 0, v[70:71]
	v_cvt_pk_bf16_f32 v5, v73, s0
	v_lshl_add_u64 v[70:71], v[70:71], 0, v[0:1]
	ds_read2_b32 v[80:81], v78 offset0:40 offset1:44
	ds_read2_b32 v[82:83], v78 offset0:48 offset1:52
	flat_store_short v[70:71], v5
	v_add_u32_e32 v70, s2, v22
	v_ashrrev_i32_e32 v71, 31, v70
	v_lshlrev_b64 v[70:71], 11, v[70:71]
	v_lshl_add_u64 v[70:71], s[40:41], 0, v[70:71]
	s_waitcnt lgkmcnt(0)
	v_cvt_pk_bf16_f32 v5, v80, s0
	v_lshl_add_u64 v[70:71], v[70:71], 0, v[0:1]
	flat_store_short v[70:71], v5
	v_add_u32_e32 v70, s2, v24
	v_ashrrev_i32_e32 v71, 31, v70
	v_lshlrev_b64 v[70:71], 11, v[70:71]
	v_lshl_add_u64 v[70:71], s[40:41], 0, v[70:71]
	v_cvt_pk_bf16_f32 v5, v81, s0
	v_lshl_add_u64 v[70:71], v[70:71], 0, v[0:1]
	flat_store_short v[70:71], v5
	v_add_u32_e32 v70, s2, v26
	v_ashrrev_i32_e32 v71, 31, v70
	v_lshlrev_b64 v[70:71], 11, v[70:71]
	v_lshl_add_u64 v[70:71], s[40:41], 0, v[70:71]
	v_cvt_pk_bf16_f32 v5, v82, s0
	v_lshl_add_u64 v[70:71], v[70:71], 0, v[0:1]
	flat_store_short v[70:71], v5
	v_add_u32_e32 v70, s2, v28
	v_ashrrev_i32_e32 v71, 31, v70
	v_lshlrev_b64 v[70:71], 11, v[70:71]
	v_lshl_add_u64 v[70:71], s[40:41], 0, v[70:71]
	v_cvt_pk_bf16_f32 v5, v83, s0
	v_lshl_add_u64 v[70:71], v[70:71], 0, v[0:1]
	ds_read2_b32 v[72:73], v78 offset0:56 offset1:60
	flat_store_short v[70:71], v5
	v_add_u32_e32 v70, s2, v30
	v_ashrrev_i32_e32 v71, 31, v70
	v_lshlrev_b64 v[70:71], 11, v[70:71]
	v_lshl_add_u64 v[70:71], s[40:41], 0, v[70:71]
	s_waitcnt lgkmcnt(0)
	v_cvt_pk_bf16_f32 v5, v72, s0
	v_lshl_add_u64 v[70:71], v[70:71], 0, v[0:1]
	flat_store_short v[70:71], v5
	v_add_u32_e32 v70, s2, v32
	v_ashrrev_i32_e32 v71, 31, v70
	v_lshlrev_b64 v[70:71], 11, v[70:71]
	v_lshl_add_u64 v[70:71], s[40:41], 0, v[70:71]
	v_cvt_pk_bf16_f32 v5, v73, s0
	v_lshl_add_u64 v[70:71], v[70:71], 0, v[0:1]
	flat_store_short v[70:71], v5
	s_mov_b64 s[2:3], 0
; DI void transpose_job(const int tid_, const float* __restrict__ src, const float* __restrict__ scale, u16* __restrict__ dst, u16* __restrict__ dst2,
;                       int K, int N, int kt, int nt, char* s0, char* s1, char* s2) {
;     ...
;   __syncthreads();
; #pragma unroll
;   for (int i = 0; i < 16; ++i) {
;     int kl = (tid >> 6) + 4 * i, nl = tid & 63;
;     int k = kt * 64 + kl, n = nt * 64 + nl;
;     tile[kl * 65 + nl] = (n < N) ? src[(size_t)k * N + n] : 0.f;
;   }
;   __syncthreads();
; DI void wprep_job(const int tid_, const Params& p, int l, int j, char* s0, char* s1, char* s2) {
;     ...
;     int q = j - 1656;
;     transpose_job(tid_, p.in[I_WB] + (size_t)l * 512 * 1024, nullptr, (u16*)(p.ws + WS_WB) + (size_t)l * 1024 * 512, nullptr, 512, 1024, q / 16, q % 16, s0, s1, s2);
.LBB0_1000:
	s_andn2_b64 vcc, exec, s[2:3]
	s_cbranch_vccnz .LBB0_1002
	s_add_i32 s2, s9, 0x2000
	s_add_i32 s3, s20, 0x200
	s_and_b32 s2, s2, 0x3c0
	s_and_b32 s3, s3, 0x7fffffc0
	v_or_b32_e32 v0, s2, v74
	v_readlane_b32 s38, v254, 54
	v_add_u32_e32 v72, s3, v2
	v_lshlrev_b32_e32 v0, 2, v0
	v_readlane_b32 s39, v254, 55
	v_ashrrev_i32_e32 v73, 31, v72
	v_lshlrev_b64 v[72:73], 12, v[72:73]
	v_lshl_add_u64 v[70:71], s[38:39], 0, v[0:1]
	v_lshl_add_u64 v[72:73], v[70:71], 0, v[72:73]
	s_waitcnt lgkmcnt(0)
	s_barrier
	flat_load_dword v206, v[72:73]
	v_add_u32_e32 v72, s3, v4
	v_ashrrev_i32_e32 v73, 31, v72
	v_lshlrev_b64 v[72:73], 12, v[72:73]
	v_add_u32_e32 v5, v75, v76
	v_lshl_add_u64 v[72:73], v[70:71], 0, v[72:73]
	flat_load_dword v207, v[72:73]
	v_add_u32_e32 v72, s3, v6
	v_ashrrev_i32_e32 v73, 31, v72
	v_lshlrev_b64 v[72:73], 12, v[72:73]
	v_lshl_add_u64 v[72:73], v[70:71], 0, v[72:73]
	flat_load_dword v208, v[72:73]
	v_add_u32_e32 v72, s3, v8
	v_ashrrev_i32_e32 v73, 31, v72
	v_lshlrev_b64 v[72:73], 12, v[72:73]
	v_lshl_add_u64 v[72:73], v[70:71], 0, v[72:73]
	flat_load_dword v209, v[72:73]
	v_add_u32_e32 v72, s3, v10
	v_ashrrev_i32_e32 v73, 31, v72
	v_lshlrev_b64 v[72:73], 12, v[72:73]
	v_lshl_add_u64 v[72:73], v[70:71], 0, v[72:73]
	flat_load_dword v210, v[72:73]
	v_add_u32_e32 v72, s3, v12
	v_ashrrev_i32_e32 v73, 31, v72
	v_lshlrev_b64 v[72:73], 12, v[72:73]
	v_lshl_add_u64 v[72:73], v[70:71], 0, v[72:73]
	flat_load_dword v211, v[72:73]
	v_add_u32_e32 v72, s3, v14
	v_ashrrev_i32_e32 v73, 31, v72
	v_lshlrev_b64 v[72:73], 12, v[72:73]
	v_lshl_add_u64 v[72:73], v[70:71], 0, v[72:73]
	s_waitcnt vmcnt(5) lgkmcnt(0)
	ds_write_b32 v5, v206
	s_waitcnt vmcnt(4)
	ds_write_b32 v5, v207 offset:1040
	s_waitcnt vmcnt(3)
	ds_write_b32 v5, v208 offset:2080
	s_waitcnt vmcnt(2)
	ds_write_b32 v5, v209 offset:3120
	s_waitcnt vmcnt(1)
	ds_write_b32 v5, v210 offset:4160
	s_waitcnt vmcnt(0)
	ds_write_b32 v5, v211 offset:5200
	flat_load_dword v206, v[72:73]
	v_add_u32_e32 v72, s3, v16
	v_ashrrev_i32_e32 v73, 31, v72
	v_lshlrev_b64 v[72:73], 12, v[72:73]
	v_add_u32_e32 v5, v75, v77
	v_lshl_add_u64 v[72:73], v[70:71], 0, v[72:73]
	flat_load_dword v207, v[72:73]
	v_add_u32_e32 v72, s3, v18
	v_ashrrev_i32_e32 v73, 31, v72
	v_lshlrev_b64 v[72:73], 12, v[72:73]
	v_lshl_add_u64 v[72:73], v[70:71], 0, v[72:73]
	flat_load_dword v208, v[72:73]
	v_add_u32_e32 v72, s3, v20
	v_ashrrev_i32_e32 v73, 31, v72
	v_lshlrev_b64 v[72:73], 12, v[72:73]
	v_lshl_add_u64 v[72:73], v[70:71], 0, v[72:73]
	flat_load_dword v209, v[72:73]
	v_add_u32_e32 v72, s3, v22
	v_ashrrev_i32_e32 v73, 31, v72
	v_lshlrev_b64 v[72:73], 12, v[72:73]
	v_lshl_add_u64 v[72:73], v[70:71], 0, v[72:73]
	flat_load_dword v210, v[72:73]
	v_add_u32_e32 v72, s3, v24
	v_ashrrev_i32_e32 v73, 31, v72
	v_lshlrev_b64 v[72:73], 12, v[72:73]
	v_lshl_add_u64 v[72:73], v[70:71], 0, v[72:73]
	flat_load_dword v211, v[72:73]
	v_add_u32_e32 v72, s3, v26
	v_ashrrev_i32_e32 v73, 31, v72
	v_lshlrev_b64 v[72:73], 12, v[72:73]
	v_lshl_add_u64 v[72:73], v[70:71], 0, v[72:73]
	flat_load_dword v212, v[72:73]
	v_add_u32_e32 v72, s3, v28
	v_ashrrev_i32_e32 v73, 31, v72
	v_lshlrev_b64 v[72:73], 12, v[72:73]
	v_lshl_add_u64 v[72:73], v[70:71], 0, v[72:73]
	flat_load_dword v213, v[72:73]
	v_add_u32_e32 v72, s3, v30
	v_ashrrev_i32_e32 v73, 31, v72
	v_lshlrev_b64 v[72:73], 12, v[72:73]
	v_lshl_add_u64 v[72:73], v[70:71], 0, v[72:73]
	flat_load_dword v214, v[72:73]
	v_add_u32_e32 v72, s3, v32
	v_ashrrev_i32_e32 v73, 31, v72
	v_lshlrev_b64 v[72:73], 12, v[72:73]
	v_lshl_add_u64 v[70:71], v[70:71], 0, v[72:73]
	flat_load_dword v215, v[70:71]
	v_add_u32_e32 v70, s2, v2
	v_ashrrev_i32_e32 v71, 31, v70
	v_lshlrev_b64 v[70:71], 10, v[70:71]
	v_lshl_add_u64 v[70:71], s[84:85], 0, v[70:71]
	s_waitcnt vmcnt(9) lgkmcnt(0)
	ds_write_b32 v5, v206
	s_waitcnt vmcnt(8)
	ds_write_b32 v5, v207 offset:1040
	s_waitcnt vmcnt(7)
	ds_write_b32 v5, v208 offset:2080
	s_waitcnt vmcnt(6)
	ds_write_b32 v5, v209 offset:3120
	s_waitcnt vmcnt(5)
	ds_write_b32 v5, v210 offset:4160
	s_waitcnt vmcnt(4)
	ds_write_b32 v5, v211 offset:5200
	s_waitcnt vmcnt(3)
	ds_write_b32 v5, v212 offset:6240
	s_waitcnt vmcnt(2)
	ds_write_b32 v5, v213 offset:7280
	s_waitcnt vmcnt(1)
	ds_write_b32 v5, v214 offset:8320
	s_waitcnt vmcnt(0)
	ds_write_b32 v5, v215 offset:9360
	s_waitcnt lgkmcnt(0)
	s_barrier
; DI void transpose_job(const int tid_, const float* __restrict__ src, const float* __restrict__ scale, u16* __restrict__ dst, u16* __restrict__ dst2,
;                       int K, int N, int kt, int nt, char* s0, char* s1, char* s2) {
;     ...
;   for (int i = 0; i < 16; ++i) {
;     int nl = (tid >> 6) + 4 * i, kl = tid & 63;
;     int k = kt * 64 + kl, n = nt * 64 + nl;
;     float v = tile[kl * 65 + nl];
;     float sc = scale ? scale[k] : 1.f;
;     dst[(size_t)n * K + k] = (u16)(pack2(v * sc, 0.f) & 0xffffu);
;     if (dst2) dst2[(size_t)n * K + k] = (u16)(pack2(v, 0.f) & 0xffffu);
;   }
	ds_read2_b32 v[72:73], v78 offset1:4
	ds_read2_b32 v[80:81], v78 offset0:8 offset1:12
	v_or_b32_e32 v0, s3, v74
	v_lshlrev_b32_e32 v0, 1, v0
	v_lshl_add_u64 v[70:71], v[70:71], 0, v[0:1]
	s_waitcnt lgkmcnt(1)
	v_cvt_pk_bf16_f32 v5, v72, s0
	flat_store_short v[70:71], v5
	v_add_u32_e32 v70, s2, v4
	v_ashrrev_i32_e32 v71, 31, v70
	v_lshlrev_b64 v[70:71], 10, v[70:71]
	v_lshl_add_u64 v[70:71], s[84:85], 0, v[70:71]
	v_cvt_pk_bf16_f32 v5, v73, s0
	v_lshl_add_u64 v[70:71], v[70:71], 0, v[0:1]
	flat_store_short v[70:71], v5
	v_add_u32_e32 v70, s2, v6
	v_ashrrev_i32_e32 v71, 31, v70
	v_lshlrev_b64 v[70:71], 10, v[70:71]
	v_lshl_add_u64 v[70:71], s[84:85], 0, v[70:71]
	s_waitcnt lgkmcnt(0)
	v_cvt_pk_bf16_f32 v5, v80, s0
	v_lshl_add_u64 v[70:71], v[70:71], 0, v[0:1]
	flat_store_short v[70:71], v5
	v_add_u32_e32 v70, s2, v8
	v_ashrrev_i32_e32 v71, 31, v70
	v_lshlrev_b64 v[70:71], 10, v[70:71]
	v_lshl_add_u64 v[70:71], s[84:85], 0, v[70:71]
	v_cvt_pk_bf16_f32 v5, v81, s0
	v_lshl_add_u64 v[70:71], v[70:71], 0, v[0:1]
	ds_read2_b32 v[72:73], v78 offset0:16 offset1:20
	flat_store_short v[70:71], v5
	v_add_u32_e32 v70, s2, v10
	v_ashrrev_i32_e32 v71, 31, v70
	v_lshlrev_b64 v[70:71], 10, v[70:71]
	v_lshl_add_u64 v[70:71], s[84:85], 0, v[70:71]
	s_waitcnt lgkmcnt(0)
	v_cvt_pk_bf16_f32 v5, v72, s0
	v_lshl_add_u64 v[70:71], v[70:71], 0, v[0:1]
	flat_store_short v[70:71], v5
	v_add_u32_e32 v70, s2, v12
	v_ashrrev_i32_e32 v71, 31, v70
	v_lshlrev_b64 v[70:71], 10, v[70:71]
	v_lshl_add_u64 v[70:71], s[84:85], 0, v[70:71]
	v_cvt_pk_bf16_f32 v5, v73, s0
	v_lshl_add_u64 v[70:71], v[70:71], 0, v[0:1]
	ds_read2_b32 v[72:73], v78 offset0:24 offset1:28
	flat_store_short v[70:71], v5
	v_add_u32_e32 v70, s2, v14
	v_ashrrev_i32_e32 v71, 31, v70
	v_lshlrev_b64 v[70:71], 10, v[70:71]
	v_lshl_add_u64 v[70:71], s[84:85], 0, v[70:71]
	s_waitcnt lgkmcnt(0)
	v_cvt_pk_bf16_f32 v5, v72, s0
	v_lshl_add_u64 v[70:71], v[70:71], 0, v[0:1]
	flat_store_short v[70:71], v5
	v_add_u32_e32 v70, s2, v16
	v_ashrrev_i32_e32 v71, 31, v70
	v_lshlrev_b64 v[70:71], 10, v[70:71]
	v_lshl_add_u64 v[70:71], s[84:85], 0, v[70:71]
	v_cvt_pk_bf16_f32 v5, v73, s0
	v_lshl_add_u64 v[70:71], v[70:71], 0, v[0:1]
	ds_read2_b32 v[72:73], v78 offset0:32 offset1:36
	flat_store_short v[70:71], v5
	v_add_u32_e32 v70, s2, v18
	v_ashrrev_i32_e32 v71, 31, v70
	v_lshlrev_b64 v[70:71], 10, v[70:71]
	v_lshl_add_u64 v[70:71], s[84:85], 0, v[70:71]
	s_waitcnt lgkmcnt(0)
	v_cvt_pk_bf16_f32 v5, v72, s0
	v_lshl_add_u64 v[70:71], v[70:71], 0, v[0:1]
	flat_store_short v[70:71], v5
	v_add_u32_e32 v70, s2, v20
	v_ashrrev_i32_e32 v71, 31, v70
	v_lshlrev_b64 v[70:71], 10, v[70:71]
	v_lshl_add_u64 v[70:71], s[84:85], 0, v[70:71]
	v_cvt_pk_bf16_f32 v5, v73, s0
	v_lshl_add_u64 v[70:71], v[70:71], 0, v[0:1]
	ds_read2_b32 v[80:81], v78 offset0:40 offset1:44
	ds_read2_b32 v[82:83], v78 offset0:48 offset1:52
	flat_store_short v[70:71], v5
	v_add_u32_e32 v70, s2, v22
	v_ashrrev_i32_e32 v71, 31, v70
	v_lshlrev_b64 v[70:71], 10, v[70:71]
	v_lshl_add_u64 v[70:71], s[84:85], 0, v[70:71]
	s_waitcnt lgkmcnt(0)
	v_cvt_pk_bf16_f32 v5, v80, s0
	v_lshl_add_u64 v[70:71], v[70:71], 0, v[0:1]
	flat_store_short v[70:71], v5
	v_add_u32_e32 v70, s2, v24
	v_ashrrev_i32_e32 v71, 31, v70
	v_lshlrev_b64 v[70:71], 10, v[70:71]
	v_lshl_add_u64 v[70:71], s[84:85], 0, v[70:71]
	v_cvt_pk_bf16_f32 v5, v81, s0
	v_lshl_add_u64 v[70:71], v[70:71], 0, v[0:1]
	flat_store_short v[70:71], v5
	v_add_u32_e32 v70, s2, v26
	v_ashrrev_i32_e32 v71, 31, v70
	v_lshlrev_b64 v[70:71], 10, v[70:71]
	v_lshl_add_u64 v[70:71], s[84:85], 0, v[70:71]
	v_cvt_pk_bf16_f32 v5, v82, s0
	v_lshl_add_u64 v[70:71], v[70:71], 0, v[0:1]
	flat_store_short v[70:71], v5
	v_add_u32_e32 v70, s2, v28
	v_ashrrev_i32_e32 v71, 31, v70
	v_lshlrev_b64 v[70:71], 10, v[70:71]
	v_lshl_add_u64 v[70:71], s[84:85], 0, v[70:71]
	v_cvt_pk_bf16_f32 v5, v83, s0
	v_lshl_add_u64 v[70:71], v[70:71], 0, v[0:1]
	ds_read2_b32 v[72:73], v78 offset0:56 offset1:60
	flat_store_short v[70:71], v5
	v_add_u32_e32 v70, s2, v30
	v_ashrrev_i32_e32 v71, 31, v70
	v_lshlrev_b64 v[70:71], 10, v[70:71]
	v_lshl_add_u64 v[70:71], s[84:85], 0, v[70:71]
	s_waitcnt lgkmcnt(0)
	v_cvt_pk_bf16_f32 v5, v72, s0
	v_lshl_add_u64 v[70:71], v[70:71], 0, v[0:1]
	flat_store_short v[70:71], v5
	v_add_u32_e32 v70, s2, v32
	v_ashrrev_i32_e32 v71, 31, v70
	v_lshlrev_b64 v[70:71], 10, v[70:71]
	v_lshl_add_u64 v[70:71], s[84:85], 0, v[70:71]
	v_cvt_pk_bf16_f32 v5, v73, s0
	v_lshl_add_u64 v[70:71], v[70:71], 0, v[0:1]
	flat_store_short v[70:71], v5

; DI void transpose_job(const int tid_, const float* __restrict__ src, const float* __restrict__ scale, u16* __restrict__ dst, u16* __restrict__ dst2,
;                       int K, int N, int kt, int nt, char* s0, char* s1, char* s2) {
;     ...
;   __syncthreads();
; #pragma unroll
;   for (int i = 0; i < 16; ++i) {
;     int kl = (tid >> 6) + 4 * i, nl = tid & 63;
;     int k = kt * 64 + kl, n = nt * 64 + nl;
;     tile[kl * 65 + nl] = (n < N) ? src[(size_t)k * N + n] : 0.f;
;   }
;   __syncthreads();
; DI void wprep_job(const int tid_, const Params& p, int l, int j, char* s0, char* s1, char* s2) {
;     ...
;     int q = j - 1528;
;     transpose_job(tid_, p.in[I_WA] + (size_t)l * 512 * 1024, nullptr, (u16*)(p.ws + WS_WA) + (size_t)l * 1024 * 512, nullptr, 512, 1024, q / 16, q % 16, s0, s1, s2);
.LBB0_1003:
	s_andn2_b64 vcc, exec, s[2:3]
	s_cbranch_vccnz .LBB0_1005
	s_add_i32 s2, s9, 0x4000
	s_add_i32 s3, s20, 0x400
	s_and_b32 s2, s2, 0x3c0
	s_and_b32 s3, s3, 0x7fffffc0
	v_or_b32_e32 v0, s2, v74
	v_add_u32_e32 v72, s3, v2
	v_lshlrev_b32_e32 v0, 2, v0
	v_ashrrev_i32_e32 v73, 31, v72
	v_lshl_add_u64 v[70:71], s[50:51], 0, v[0:1]
	v_lshlrev_b64 v[72:73], 12, v[72:73]
	v_lshl_add_u64 v[72:73], v[70:71], 0, v[72:73]
	s_waitcnt lgkmcnt(0)
	s_barrier
	flat_load_dword v206, v[72:73]
	v_add_u32_e32 v72, s3, v4
	v_ashrrev_i32_e32 v73, 31, v72
	v_lshlrev_b64 v[72:73], 12, v[72:73]
	v_add_u32_e32 v5, v75, v76
	v_lshl_add_u64 v[72:73], v[70:71], 0, v[72:73]
	flat_load_dword v207, v[72:73]
	v_add_u32_e32 v72, s3, v6
	v_ashrrev_i32_e32 v73, 31, v72
	v_lshlrev_b64 v[72:73], 12, v[72:73]
	v_lshl_add_u64 v[72:73], v[70:71], 0, v[72:73]
	flat_load_dword v208, v[72:73]
	v_add_u32_e32 v72, s3, v8
	v_ashrrev_i32_e32 v73, 31, v72
	v_lshlrev_b64 v[72:73], 12, v[72:73]
	v_lshl_add_u64 v[72:73], v[70:71], 0, v[72:73]
	flat_load_dword v209, v[72:73]
	v_add_u32_e32 v72, s3, v10
	v_ashrrev_i32_e32 v73, 31, v72
	v_lshlrev_b64 v[72:73], 12, v[72:73]
	v_lshl_add_u64 v[72:73], v[70:71], 0, v[72:73]
	flat_load_dword v210, v[72:73]
	v_add_u32_e32 v72, s3, v12
	v_ashrrev_i32_e32 v73, 31, v72
	v_lshlrev_b64 v[72:73], 12, v[72:73]
	v_lshl_add_u64 v[72:73], v[70:71], 0, v[72:73]
	flat_load_dword v211, v[72:73]
	v_add_u32_e32 v72, s3, v14
	v_ashrrev_i32_e32 v73, 31, v72
	v_lshlrev_b64 v[72:73], 12, v[72:73]
	v_lshl_add_u64 v[72:73], v[70:71], 0, v[72:73]
	s_waitcnt vmcnt(5) lgkmcnt(0)
	ds_write_b32 v5, v206
	s_waitcnt vmcnt(4)
	ds_write_b32 v5, v207 offset:1040
	s_waitcnt vmcnt(3)
	ds_write_b32 v5, v208 offset:2080
	s_waitcnt vmcnt(2)
	ds_write_b32 v5, v209 offset:3120
	s_waitcnt vmcnt(1)
	ds_write_b32 v5, v210 offset:4160
	s_waitcnt vmcnt(0)
	ds_write_b32 v5, v211 offset:5200
	flat_load_dword v206, v[72:73]
	v_add_u32_e32 v72, s3, v16
	v_ashrrev_i32_e32 v73, 31, v72
	v_lshlrev_b64 v[72:73], 12, v[72:73]
	v_add_u32_e32 v5, v75, v77
	v_lshl_add_u64 v[72:73], v[70:71], 0, v[72:73]
	flat_load_dword v207, v[72:73]
	v_add_u32_e32 v72, s3, v18
	v_ashrrev_i32_e32 v73, 31, v72
	v_lshlrev_b64 v[72:73], 12, v[72:73]
	v_lshl_add_u64 v[72:73], v[70:71], 0, v[72:73]
	flat_load_dword v208, v[72:73]
	v_add_u32_e32 v72, s3, v20
	v_ashrrev_i32_e32 v73, 31, v72
	v_lshlrev_b64 v[72:73], 12, v[72:73]
	v_lshl_add_u64 v[72:73], v[70:71], 0, v[72:73]
	flat_load_dword v209, v[72:73]
	v_add_u32_e32 v72, s3, v22
	v_ashrrev_i32_e32 v73, 31, v72
	v_lshlrev_b64 v[72:73], 12, v[72:73]
	v_lshl_add_u64 v[72:73], v[70:71], 0, v[72:73]
	flat_load_dword v210, v[72:73]
	v_add_u32_e32 v72, s3, v24
	v_ashrrev_i32_e32 v73, 31, v72
	v_lshlrev_b64 v[72:73], 12, v[72:73]
	v_lshl_add_u64 v[72:73], v[70:71], 0, v[72:73]
	flat_load_dword v211, v[72:73]
	v_add_u32_e32 v72, s3, v26
	v_ashrrev_i32_e32 v73, 31, v72
	v_lshlrev_b64 v[72:73], 12, v[72:73]
	v_lshl_add_u64 v[72:73], v[70:71], 0, v[72:73]
	flat_load_dword v212, v[72:73]
	v_add_u32_e32 v72, s3, v28
	v_ashrrev_i32_e32 v73, 31, v72
	v_lshlrev_b64 v[72:73], 12, v[72:73]
	v_lshl_add_u64 v[72:73], v[70:71], 0, v[72:73]
	flat_load_dword v213, v[72:73]
	v_add_u32_e32 v72, s3, v30
	v_ashrrev_i32_e32 v73, 31, v72
	v_lshlrev_b64 v[72:73], 12, v[72:73]
	v_lshl_add_u64 v[72:73], v[70:71], 0, v[72:73]
	flat_load_dword v214, v[72:73]
	v_add_u32_e32 v72, s3, v32
	v_ashrrev_i32_e32 v73, 31, v72
	v_lshlrev_b64 v[72:73], 12, v[72:73]
	v_lshl_add_u64 v[70:71], v[70:71], 0, v[72:73]
	flat_load_dword v215, v[70:71]
	v_add_u32_e32 v70, s2, v2
	v_ashrrev_i32_e32 v71, 31, v70
	v_lshlrev_b64 v[70:71], 10, v[70:71]
	v_lshl_add_u64 v[70:71], s[86:87], 0, v[70:71]
	s_waitcnt vmcnt(9) lgkmcnt(0)
	ds_write_b32 v5, v206
	s_waitcnt vmcnt(8)
	ds_write_b32 v5, v207 offset:1040
	s_waitcnt vmcnt(7)
	ds_write_b32 v5, v208 offset:2080
	s_waitcnt vmcnt(6)
	ds_write_b32 v5, v209 offset:3120
	s_waitcnt vmcnt(5)
	ds_write_b32 v5, v210 offset:4160
	s_waitcnt vmcnt(4)
	ds_write_b32 v5, v211 offset:5200
	s_waitcnt vmcnt(3)
	ds_write_b32 v5, v212 offset:6240
	s_waitcnt vmcnt(2)
	ds_write_b32 v5, v213 offset:7280
	s_waitcnt vmcnt(1)
	ds_write_b32 v5, v214 offset:8320
	s_waitcnt vmcnt(0)
	ds_write_b32 v5, v215 offset:9360
	s_waitcnt lgkmcnt(0)
	s_barrier
; DI void transpose_job(const int tid_, const float* __restrict__ src, const float* __restrict__ scale, u16* __restrict__ dst, u16* __restrict__ dst2,
;                       int K, int N, int kt, int nt, char* s0, char* s1, char* s2) {
;     ...
;   for (int i = 0; i < 16; ++i) {
;     int nl = (tid >> 6) + 4 * i, kl = tid & 63;
;     int k = kt * 64 + kl, n = nt * 64 + nl;
;     float v = tile[kl * 65 + nl];
;     float sc = scale ? scale[k] : 1.f;
;     dst[(size_t)n * K + k] = (u16)(pack2(v * sc, 0.f) & 0xffffu);
;     if (dst2) dst2[(size_t)n * K + k] = (u16)(pack2(v, 0.f) & 0xffffu);
;   }
	ds_read2_b32 v[72:73], v78 offset1:4
	ds_read2_b32 v[80:81], v78 offset0:8 offset1:12
	v_or_b32_e32 v0, s3, v74
	v_lshlrev_b32_e32 v0, 1, v0
	v_lshl_add_u64 v[70:71], v[70:71], 0, v[0:1]
	s_waitcnt lgkmcnt(1)
	v_cvt_pk_bf16_f32 v5, v72, s0
	flat_store_short v[70:71], v5
	v_add_u32_e32 v70, s2, v4
	v_ashrrev_i32_e32 v71, 31, v70
	v_lshlrev_b64 v[70:71], 10, v[70:71]
	v_lshl_add_u64 v[70:71], s[86:87], 0, v[70:71]
	v_cvt_pk_bf16_f32 v5, v73, s0
	v_lshl_add_u64 v[70:71], v[70:71], 0, v[0:1]
	flat_store_short v[70:71], v5
	v_add_u32_e32 v70, s2, v6
	v_ashrrev_i32_e32 v71, 31, v70
	v_lshlrev_b64 v[70:71], 10, v[70:71]
	v_lshl_add_u64 v[70:71], s[86:87], 0, v[70:71]
	s_waitcnt lgkmcnt(0)
	v_cvt_pk_bf16_f32 v5, v80, s0
	v_lshl_add_u64 v[70:71], v[70:71], 0, v[0:1]
	flat_store_short v[70:71], v5
	v_add_u32_e32 v70, s2, v8
	v_ashrrev_i32_e32 v71, 31, v70
	v_lshlrev_b64 v[70:71], 10, v[70:71]
	v_lshl_add_u64 v[70:71], s[86:87], 0, v[70:71]
	v_cvt_pk_bf16_f32 v5, v81, s0
	v_lshl_add_u64 v[70:71], v[70:71], 0, v[0:1]
	ds_read2_b32 v[72:73], v78 offset0:16 offset1:20
	flat_store_short v[70:71], v5
	v_add_u32_e32 v70, s2, v10
	v_ashrrev_i32_e32 v71, 31, v70
	v_lshlrev_b64 v[70:71], 10, v[70:71]
	v_lshl_add_u64 v[70:71], s[86:87], 0, v[70:71]
	s_waitcnt lgkmcnt(0)
	v_cvt_pk_bf16_f32 v5, v72, s0
	v_lshl_add_u64 v[70:71], v[70:71], 0, v[0:1]
	flat_store_short v[70:71], v5
	v_add_u32_e32 v70, s2, v12
	v_ashrrev_i32_e32 v71, 31, v70
	v_lshlrev_b64 v[70:71], 10, v[70:71]
	v_lshl_add_u64 v[70:71], s[86:87], 0, v[70:71]
	v_cvt_pk_bf16_f32 v5, v73, s0
	v_lshl_add_u64 v[70:71], v[70:71], 0, v[0:1]
	ds_read2_b32 v[72:73], v78 offset0:24 offset1:28
	flat_store_short v[70:71], v5
	v_add_u32_e32 v70, s2, v14
	v_ashrrev_i32_e32 v71, 31, v70
	v_lshlrev_b64 v[70:71], 10, v[70:71]
	v_lshl_add_u64 v[70:71], s[86:87], 0, v[70:71]
	s_waitcnt lgkmcnt(0)
	v_cvt_pk_bf16_f32 v5, v72, s0
	v_lshl_add_u64 v[70:71], v[70:71], 0, v[0:1]
	flat_store_short v[70:71], v5
	v_add_u32_e32 v70, s2, v16
	v_ashrrev_i32_e32 v71, 31, v70
	v_lshlrev_b64 v[70:71], 10, v[70:71]
	v_lshl_add_u64 v[70:71], s[86:87], 0, v[70:71]
	v_cvt_pk_bf16_f32 v5, v73, s0
	v_lshl_add_u64 v[70:71], v[70:71], 0, v[0:1]
	ds_read2_b32 v[72:73], v78 offset0:32 offset1:36
	flat_store_short v[70:71], v5
	v_add_u32_e32 v70, s2, v18
	v_ashrrev_i32_e32 v71, 31, v70
	v_lshlrev_b64 v[70:71], 10, v[70:71]
	v_lshl_add_u64 v[70:71], s[86:87], 0, v[70:71]
	s_waitcnt lgkmcnt(0)
	v_cvt_pk_bf16_f32 v5, v72, s0
	v_lshl_add_u64 v[70:71], v[70:71], 0, v[0:1]
	flat_store_short v[70:71], v5
	v_add_u32_e32 v70, s2, v20
	v_ashrrev_i32_e32 v71, 31, v70
	v_lshlrev_b64 v[70:71], 10, v[70:71]
	v_lshl_add_u64 v[70:71], s[86:87], 0, v[70:71]
	v_cvt_pk_bf16_f32 v5, v73, s0
	v_lshl_add_u64 v[70:71], v[70:71], 0, v[0:1]
	ds_read2_b32 v[80:81], v78 offset0:40 offset1:44
	ds_read2_b32 v[82:83], v78 offset0:48 offset1:52
	flat_store_short v[70:71], v5
	v_add_u32_e32 v70, s2, v22
	v_ashrrev_i32_e32 v71, 31, v70
	v_lshlrev_b64 v[70:71], 10, v[70:71]
	v_lshl_add_u64 v[70:71], s[86:87], 0, v[70:71]
	s_waitcnt lgkmcnt(0)
	v_cvt_pk_bf16_f32 v5, v80, s0
	v_lshl_add_u64 v[70:71], v[70:71], 0, v[0:1]
	flat_store_short v[70:71], v5
	v_add_u32_e32 v70, s2, v24
	v_ashrrev_i32_e32 v71, 31, v70
	v_lshlrev_b64 v[70:71], 10, v[70:71]
	v_lshl_add_u64 v[70:71], s[86:87], 0, v[70:71]
	v_cvt_pk_bf16_f32 v5, v81, s0
	v_lshl_add_u64 v[70:71], v[70:71], 0, v[0:1]
	flat_store_short v[70:71], v5
	v_add_u32_e32 v70, s2, v26
	v_ashrrev_i32_e32 v71, 31, v70
	v_lshlrev_b64 v[70:71], 10, v[70:71]
	v_lshl_add_u64 v[70:71], s[86:87], 0, v[70:71]
	v_cvt_pk_bf16_f32 v5, v82, s0
	v_lshl_add_u64 v[70:71], v[70:71], 0, v[0:1]
	flat_store_short v[70:71], v5
	v_add_u32_e32 v70, s2, v28
	v_ashrrev_i32_e32 v71, 31, v70
	v_lshlrev_b64 v[70:71], 10, v[70:71]
	v_lshl_add_u64 v[70:71], s[86:87], 0, v[70:71]
	v_cvt_pk_bf16_f32 v5, v83, s0
	v_lshl_add_u64 v[70:71], v[70:71], 0, v[0:1]
	ds_read2_b32 v[72:73], v78 offset0:56 offset1:60
	flat_store_short v[70:71], v5
	v_add_u32_e32 v70, s2, v30
	v_ashrrev_i32_e32 v71, 31, v70
	v_lshlrev_b64 v[70:71], 10, v[70:71]
	v_lshl_add_u64 v[70:71], s[86:87], 0, v[70:71]
	s_waitcnt lgkmcnt(0)
	v_cvt_pk_bf16_f32 v5, v72, s0
	v_lshl_add_u64 v[70:71], v[70:71], 0, v[0:1]
	flat_store_short v[70:71], v5
	v_add_u32_e32 v70, s2, v32
	v_ashrrev_i32_e32 v71, 31, v70
	v_lshlrev_b64 v[70:71], 10, v[70:71]
	v_lshl_add_u64 v[70:71], s[86:87], 0, v[70:71]
	v_cvt_pk_bf16_f32 v5, v73, s0
	v_lshl_add_u64 v[70:71], v[70:71], 0, v[0:1]
	flat_store_short v[70:71], v5

; DI void transpose_job(const int tid_, const float* __restrict__ src, const float* __restrict__ scale, u16* __restrict__ dst, u16* __restrict__ dst2,
;                       int K, int N, int kt, int nt, char* s0, char* s1, char* s2) {
;     ...
;   __syncthreads();
; #pragma unroll
;   for (int i = 0; i < 16; ++i) {
;     int kl = (tid >> 6) + 4 * i, nl = tid & 63;
;     int k = kt * 64 + kl, n = nt * 64 + nl;
;     tile[kl * 65 + nl] = (n < N) ? src[(size_t)k * N + n] : 0.f;
;   }
;   __syncthreads();
; #pragma unroll
;   for (int i = 0; i < 16; ++i) {
;     int nl = (tid >> 6) + 4 * i, kl = tid & 63;
;     int k = kt * 64 + kl, n = nt * 64 + nl;
;     float v = tile[kl * 65 + nl];
;     float sc = scale ? scale[k] : 1.f;
; DI void wprep_job(const int tid_, const Params& p, int l, int j, char* s0, char* s1, char* s2) {
;     ...
;     int q = j - 1464;
;     transpose_job(tid_, p.in[I_WUKV] + (size_t)l * 256 * 1024, p.in[I_KVNORM] + l * 256, (u16*)(p.ws + WS_WKVF) + (size_t)l * 1024 * 256,
;                   (u16*)(p.ws + WS_WKVP) + (size_t)l * 1024 * 256, 256, 1024, q / 16, q % 16, s0, s1, s2);
.LBB0_1006:
	s_andn2_b64 vcc, exec, s[2:3]
	s_cbranch_vccnz .LBB0_1040
	s_add_i32 s2, s9, 0x5000
	s_add_i32 s3, s20, 0x500
	s_and_b32 s2, s2, 0x3c0
	s_and_b32 s3, s3, 0x7fffffc0
	v_or_b32_e32 v0, s2, v74
	v_add_u32_e32 v72, s3, v2
	v_lshlrev_b32_e32 v0, 2, v0
	v_ashrrev_i32_e32 v73, 31, v72
	v_lshl_add_u64 v[70:71], s[48:49], 0, v[0:1]
	v_lshlrev_b64 v[72:73], 12, v[72:73]
	v_lshl_add_u64 v[72:73], v[70:71], 0, v[72:73]
	s_waitcnt lgkmcnt(0)
	s_barrier
	flat_load_dword v206, v[72:73]
	v_add_u32_e32 v72, s3, v4
	v_ashrrev_i32_e32 v73, 31, v72
	v_lshlrev_b64 v[72:73], 12, v[72:73]
	v_add_u32_e32 v5, v75, v76
	v_lshl_add_u64 v[72:73], v[70:71], 0, v[72:73]
	v_cndmask_b32_e64 v9, 0, 1, s[92:93]
	v_cmp_ne_u32_e64 s[38:39], 1, v9
	s_andn2_b64 vcc, exec, s[92:93]
	v_mov_b32_e32 v9, 1.0
	flat_load_dword v207, v[72:73]
	v_add_u32_e32 v72, s3, v6
	v_ashrrev_i32_e32 v73, 31, v72
	v_lshlrev_b64 v[72:73], 12, v[72:73]
	v_lshl_add_u64 v[72:73], v[70:71], 0, v[72:73]
	flat_load_dword v208, v[72:73]
	v_add_u32_e32 v72, s3, v8
	v_ashrrev_i32_e32 v73, 31, v72
	v_lshlrev_b64 v[72:73], 12, v[72:73]
	v_lshl_add_u64 v[72:73], v[70:71], 0, v[72:73]
	flat_load_dword v209, v[72:73]
	v_add_u32_e32 v72, s3, v10
	v_ashrrev_i32_e32 v73, 31, v72
	v_lshlrev_b64 v[72:73], 12, v[72:73]
	v_lshl_add_u64 v[72:73], v[70:71], 0, v[72:73]
	flat_load_dword v210, v[72:73]
	v_add_u32_e32 v72, s3, v12
	v_ashrrev_i32_e32 v73, 31, v72
	v_lshlrev_b64 v[72:73], 12, v[72:73]
	v_lshl_add_u64 v[72:73], v[70:71], 0, v[72:73]
	flat_load_dword v211, v[72:73]
	v_add_u32_e32 v72, s3, v14
	v_ashrrev_i32_e32 v73, 31, v72
	v_lshlrev_b64 v[72:73], 12, v[72:73]
	v_lshl_add_u64 v[72:73], v[70:71], 0, v[72:73]
	s_waitcnt vmcnt(5) lgkmcnt(0)
	ds_write_b32 v5, v206
	s_waitcnt vmcnt(4)
	ds_write_b32 v5, v207 offset:1040
	s_waitcnt vmcnt(3)
	ds_write_b32 v5, v208 offset:2080
	s_waitcnt vmcnt(2)
	ds_write_b32 v5, v209 offset:3120
	s_waitcnt vmcnt(1)
	ds_write_b32 v5, v210 offset:4160
	s_waitcnt vmcnt(0)
	ds_write_b32 v5, v211 offset:5200
	flat_load_dword v206, v[72:73]
	v_add_u32_e32 v72, s3, v16
	v_ashrrev_i32_e32 v73, 31, v72
	v_lshlrev_b64 v[72:73], 12, v[72:73]
	v_add_u32_e32 v5, v75, v77
	v_lshl_add_u64 v[72:73], v[70:71], 0, v[72:73]
	flat_load_dword v207, v[72:73]
	v_add_u32_e32 v72, s3, v18
	v_ashrrev_i32_e32 v73, 31, v72
	v_lshlrev_b64 v[72:73], 12, v[72:73]
	v_lshl_add_u64 v[72:73], v[70:71], 0, v[72:73]
	flat_load_dword v208, v[72:73]
	v_add_u32_e32 v72, s3, v20
	v_ashrrev_i32_e32 v73, 31, v72
	v_lshlrev_b64 v[72:73], 12, v[72:73]
	v_lshl_add_u64 v[72:73], v[70:71], 0, v[72:73]
	flat_load_dword v209, v[72:73]
	v_add_u32_e32 v72, s3, v22
	v_ashrrev_i32_e32 v73, 31, v72
	v_lshlrev_b64 v[72:73], 12, v[72:73]
	v_lshl_add_u64 v[72:73], v[70:71], 0, v[72:73]
	flat_load_dword v210, v[72:73]
	v_add_u32_e32 v72, s3, v24
	v_ashrrev_i32_e32 v73, 31, v72
	v_lshlrev_b64 v[72:73], 12, v[72:73]
	v_lshl_add_u64 v[72:73], v[70:71], 0, v[72:73]
	flat_load_dword v211, v[72:73]
	v_add_u32_e32 v72, s3, v26
	v_ashrrev_i32_e32 v73, 31, v72
	v_lshlrev_b64 v[72:73], 12, v[72:73]
	v_lshl_add_u64 v[72:73], v[70:71], 0, v[72:73]
	flat_load_dword v212, v[72:73]
	v_add_u32_e32 v72, s3, v28
	v_ashrrev_i32_e32 v73, 31, v72
	v_lshlrev_b64 v[72:73], 12, v[72:73]
	v_lshl_add_u64 v[72:73], v[70:71], 0, v[72:73]
	flat_load_dword v213, v[72:73]
	v_add_u32_e32 v72, s3, v30
	v_ashrrev_i32_e32 v73, 31, v72
	v_lshlrev_b64 v[72:73], 12, v[72:73]
	v_lshl_add_u64 v[72:73], v[70:71], 0, v[72:73]
	flat_load_dword v214, v[72:73]
	v_add_u32_e32 v72, s3, v32
	v_ashrrev_i32_e32 v73, 31, v72
	v_lshlrev_b64 v[72:73], 12, v[72:73]
	v_lshl_add_u64 v[70:71], v[70:71], 0, v[72:73]
	flat_load_dword v215, v[70:71]
	s_waitcnt vmcnt(9) lgkmcnt(0)
	ds_write_b32 v5, v206
	s_waitcnt vmcnt(8)
	ds_write_b32 v5, v207 offset:1040
	s_waitcnt vmcnt(7)
	ds_write_b32 v5, v208 offset:2080
	s_waitcnt vmcnt(6)
	ds_write_b32 v5, v209 offset:3120
	s_waitcnt vmcnt(5)
	ds_write_b32 v5, v210 offset:4160
	s_waitcnt vmcnt(4)
	ds_write_b32 v5, v211 offset:5200
	s_waitcnt vmcnt(3)
	ds_write_b32 v5, v212 offset:6240
	s_waitcnt vmcnt(2)
	ds_write_b32 v5, v213 offset:7280
	s_waitcnt vmcnt(1)
	ds_write_b32 v5, v214 offset:8320
	s_waitcnt vmcnt(0)
	ds_write_b32 v5, v215 offset:9360
	s_waitcnt lgkmcnt(0)
	s_barrier
	ds_read_b32 v7, v78
	v_or_b32_e32 v0, s3, v74
	v_lshl_add_u64 v[70:71], v[0:1], 2, s[46:47]
	v_mov_b32_e32 v5, 1.0
	s_cbranch_vccnz .LBB0_1009
	flat_load_dword v9, v[70:71]

; DI void transpose_job(const int tid_, const float* __restrict__ src, const float* __restrict__ scale, u16* __restrict__ dst, u16* __restrict__ dst2,
;                       int K, int N, int kt, int nt, char* s0, char* s1, char* s2) {
;     ...
;   __syncthreads();
; #pragma unroll
;   for (int i = 0; i < 16; ++i) {
;     int kl = (tid >> 6) + 4 * i, nl = tid & 63;
;     int k = kt * 64 + kl, n = nt * 64 + nl;
;     tile[kl * 65 + nl] = (n < N) ? src[(size_t)k * N + n] : 0.f;
;   }
;   __syncthreads();
; #pragma unroll
;   for (int i = 0; i < 16; ++i) {
;     int nl = (tid >> 6) + 4 * i, kl = tid & 63;
;     int k = kt * 64 + kl, n = nt * 64 + nl;
;     float v = tile[kl * 65 + nl];
;     float sc = scale ? scale[k] : 1.f;
;     dst[(size_t)n * K + k] = (u16)(pack2(v * sc, 0.f) & 0xffffu);
;     if (dst2) dst2[(size_t)n * K + k] = (u16)(pack2(v, 0.f) & 0xffffu);
;   }
; DI void wprep_job(const int tid_, const Params& p, int l, int j, char* s0, char* s1, char* s2) {
;     ...
;     transpose_job(tid_, p.in[I_A2] + (size_t)l * 64 * 512, nullptr, (u16*)(p.ws + WS_A2) + (size_t)l * 512 * 64, nullptr, 64, 512, 0, j - 1384, s0, s1, s2);
.LBB0_1076:
	s_andn2_b64 vcc, exec, s[2:3]
	s_cbranch_vccnz .LBB0_1078
	v_add_u32_e32 v0, s9, v74
	v_add_u32_e32 v0, 0x6400, v0
	v_lshl_add_u64 v[70:71], v[0:1], 2, s[30:31]
	v_lshl_add_u64 v[72:73], v[70:71], 0, v[34:35]
	s_waitcnt lgkmcnt(0)
	s_barrier
	flat_load_dword v206, v[72:73]
	v_add_u32_e32 v5, v75, v76
	v_lshl_add_u64 v[72:73], v[70:71], 0, v[36:37]
	flat_load_dword v207, v[72:73]
	v_lshl_add_u64 v[72:73], v[70:71], 0, v[38:39]
	flat_load_dword v208, v[72:73]
	v_lshl_add_u64 v[72:73], v[70:71], 0, v[40:41]
	flat_load_dword v209, v[72:73]
	v_lshl_add_u64 v[72:73], v[70:71], 0, v[42:43]
	flat_load_dword v210, v[72:73]
	v_lshl_add_u64 v[72:73], v[70:71], 0, v[44:45]
	flat_load_dword v211, v[72:73]
	v_lshl_add_u64 v[72:73], v[70:71], 0, v[46:47]
	s_waitcnt vmcnt(5) lgkmcnt(0)
	ds_write_b32 v5, v206
	s_waitcnt vmcnt(4)
	ds_write_b32 v5, v207 offset:1040
	s_waitcnt vmcnt(3)
	ds_write_b32 v5, v208 offset:2080
	s_waitcnt vmcnt(2)
	ds_write_b32 v5, v209 offset:3120
	s_waitcnt vmcnt(1)
	ds_write_b32 v5, v210 offset:4160
	s_waitcnt vmcnt(0)
	ds_write_b32 v5, v211 offset:5200
	flat_load_dword v206, v[72:73]
	v_add_u32_e32 v5, v75, v77
	v_lshl_add_u64 v[72:73], v[70:71], 0, v[48:49]
	flat_load_dword v207, v[72:73]
	v_lshl_add_u64 v[72:73], v[70:71], 0, v[50:51]
	flat_load_dword v208, v[72:73]
	v_lshl_add_u64 v[72:73], v[70:71], 0, v[52:53]
	flat_load_dword v209, v[72:73]
	v_lshl_add_u64 v[72:73], v[70:71], 0, v[54:55]
	flat_load_dword v210, v[72:73]
	v_lshl_add_u64 v[72:73], v[70:71], 0, v[56:57]
	flat_load_dword v211, v[72:73]
	v_lshl_add_u64 v[72:73], v[70:71], 0, v[58:59]
	flat_load_dword v212, v[72:73]
	v_lshl_add_u64 v[72:73], v[70:71], 0, v[60:61]
	flat_load_dword v213, v[72:73]
	v_lshl_add_u64 v[72:73], v[70:71], 0, v[62:63]
	v_lshl_add_u64 v[70:71], v[70:71], 0, v[64:65]
	flat_load_dword v214, v[72:73]
	flat_load_dword v215, v[70:71]
	s_waitcnt vmcnt(9) lgkmcnt(0)
	ds_write_b32 v5, v206
	s_waitcnt vmcnt(8)
	ds_write_b32 v5, v207 offset:1040
	s_waitcnt vmcnt(7)
	ds_write_b32 v5, v208 offset:2080
	s_waitcnt vmcnt(6)
	ds_write_b32 v5, v209 offset:3120
	s_waitcnt vmcnt(5)
	ds_write_b32 v5, v210 offset:4160
	s_waitcnt vmcnt(4)
	ds_write_b32 v5, v211 offset:5200
	s_waitcnt vmcnt(3)
	ds_write_b32 v5, v212 offset:6240
	s_waitcnt vmcnt(2)
	ds_write_b32 v5, v213 offset:7280
	s_waitcnt vmcnt(1)
	ds_write_b32 v5, v214 offset:8320
	s_waitcnt vmcnt(0)
	ds_write_b32 v5, v215 offset:9360
	s_waitcnt lgkmcnt(0)
	s_barrier
	v_add_u32_e32 v0, s9, v2
	ds_read2_b32 v[72:73], v78 offset1:4
	ds_read2_b32 v[80:81], v78 offset0:8 offset1:12
	v_add_u32_e32 v70, 0x6400, v0
	v_ashrrev_i32_e32 v71, 31, v70
	v_lshlrev_b64 v[70:71], 7, v[70:71]
	s_waitcnt lgkmcnt(1)
	v_cvt_pk_bf16_f32 v5, v72, s0
	v_lshl_add_u64 v[70:71], v[66:67], 0, v[70:71]
	flat_store_short v[70:71], v5
	v_add_u32_e32 v70, 0x6404, v0
	v_ashrrev_i32_e32 v71, 31, v70
	v_lshlrev_b64 v[70:71], 7, v[70:71]
	v_cvt_pk_bf16_f32 v5, v73, s0
	v_lshl_add_u64 v[70:71], v[66:67], 0, v[70:71]
	flat_store_short v[70:71], v5
	v_add_u32_e32 v70, 0x6408, v0
	v_ashrrev_i32_e32 v71, 31, v70
	v_lshlrev_b64 v[70:71], 7, v[70:71]
	s_waitcnt lgkmcnt(0)
	v_cvt_pk_bf16_f32 v5, v80, s0
	v_lshl_add_u64 v[70:71], v[66:67], 0, v[70:71]
	flat_store_short v[70:71], v5
	v_add_u32_e32 v70, 0x640c, v0
	v_ashrrev_i32_e32 v71, 31, v70
	v_lshlrev_b64 v[70:71], 7, v[70:71]
	ds_read2_b32 v[72:73], v78 offset0:16 offset1:20
	v_cvt_pk_bf16_f32 v5, v81, s0
	v_lshl_add_u64 v[70:71], v[66:67], 0, v[70:71]
	flat_store_short v[70:71], v5
	v_add_u32_e32 v70, 0x6410, v0
	v_ashrrev_i32_e32 v71, 31, v70
	v_lshlrev_b64 v[70:71], 7, v[70:71]
	s_waitcnt lgkmcnt(0)
	v_cvt_pk_bf16_f32 v5, v72, s0
	v_lshl_add_u64 v[70:71], v[66:67], 0, v[70:71]
	flat_store_short v[70:71], v5
	v_add_u32_e32 v70, 0x6414, v0
	v_ashrrev_i32_e32 v71, 31, v70
	v_cvt_pk_bf16_f32 v5, v73, s0
	v_lshlrev_b64 v[70:71], 7, v[70:71]
	ds_read2_b32 v[72:73], v78 offset0:24 offset1:28
	v_lshl_add_u64 v[70:71], v[66:67], 0, v[70:71]
	flat_store_short v[70:71], v5
	v_add_u32_e32 v70, 0x6418, v0
	v_ashrrev_i32_e32 v71, 31, v70
	v_lshlrev_b64 v[70:71], 7, v[70:71]
	s_waitcnt lgkmcnt(0)
	v_cvt_pk_bf16_f32 v5, v72, s0
	v_lshl_add_u64 v[70:71], v[66:67], 0, v[70:71]
	flat_store_short v[70:71], v5
	v_add_u32_e32 v70, 0x641c, v0
	v_ashrrev_i32_e32 v71, 31, v70
	v_cvt_pk_bf16_f32 v5, v73, s0
	v_lshlrev_b64 v[70:71], 7, v[70:71]
	ds_read2_b32 v[72:73], v78 offset0:32 offset1:36
	v_lshl_add_u64 v[70:71], v[66:67], 0, v[70:71]
	flat_store_short v[70:71], v5
	v_add_u32_e32 v70, 0x6420, v0
	v_ashrrev_i32_e32 v71, 31, v70
	v_lshlrev_b64 v[70:71], 7, v[70:71]
	s_waitcnt lgkmcnt(0)
	v_cvt_pk_bf16_f32 v5, v72, s0
	v_lshl_add_u64 v[70:71], v[66:67], 0, v[70:71]
	flat_store_short v[70:71], v5
	v_add_u32_e32 v70, 0x6424, v0
	v_ashrrev_i32_e32 v71, 31, v70
	v_lshlrev_b64 v[70:71], 7, v[70:71]
	ds_read2_b32 v[80:81], v78 offset0:40 offset1:44
	ds_read2_b32 v[82:83], v78 offset0:48 offset1:52
	v_cvt_pk_bf16_f32 v5, v73, s0
	v_lshl_add_u64 v[70:71], v[66:67], 0, v[70:71]
	flat_store_short v[70:71], v5
	v_add_u32_e32 v70, 0x6428, v0
	v_ashrrev_i32_e32 v71, 31, v70
	v_lshlrev_b64 v[70:71], 7, v[70:71]
	s_waitcnt lgkmcnt(0)
	v_cvt_pk_bf16_f32 v5, v80, s0
	v_lshl_add_u64 v[70:71], v[66:67], 0, v[70:71]
	flat_store_short v[70:71], v5
	v_add_u32_e32 v70, 0x642c, v0
	v_ashrrev_i32_e32 v71, 31, v70
	v_lshlrev_b64 v[70:71], 7, v[70:71]
	v_cvt_pk_bf16_f32 v5, v81, s0
	v_lshl_add_u64 v[70:71], v[66:67], 0, v[70:71]
	flat_store_short v[70:71], v5
	v_add_u32_e32 v70, 0x6430, v0
	v_ashrrev_i32_e32 v71, 31, v70
	v_lshlrev_b64 v[70:71], 7, v[70:71]
	v_cvt_pk_bf16_f32 v5, v82, s0
	v_lshl_add_u64 v[70:71], v[66:67], 0, v[70:71]
	flat_store_short v[70:71], v5
	v_add_u32_e32 v70, 0x6434, v0
	v_ashrrev_i32_e32 v71, 31, v70
	v_lshlrev_b64 v[70:71], 7, v[70:71]
	ds_read2_b32 v[72:73], v78 offset0:56 offset1:60
	v_cvt_pk_bf16_f32 v5, v83, s0
	v_lshl_add_u64 v[70:71], v[66:67], 0, v[70:71]
	flat_store_short v[70:71], v5
	v_add_u32_e32 v70, 0x6438, v0
	v_ashrrev_i32_e32 v71, 31, v70
	v_lshlrev_b64 v[70:71], 7, v[70:71]
	s_waitcnt lgkmcnt(0)
	v_cvt_pk_bf16_f32 v5, v72, s0
	v_lshl_add_u64 v[70:71], v[66:67], 0, v[70:71]
	flat_store_short v[70:71], v5
	v_add_u32_e32 v70, 0x643c, v0
	v_ashrrev_i32_e32 v71, 31, v70
	v_lshlrev_b64 v[70:71], 7, v[70:71]
	v_cvt_pk_bf16_f32 v0, v73, s0
	v_lshl_add_u64 v[70:71], v[66:67], 0, v[70:71]
	flat_store_short v[70:71], v0

; DI void transpose_job(const int tid_, const float* __restrict__ src, const float* __restrict__ scale, u16* __restrict__ dst, u16* __restrict__ dst2,
;                       int K, int N, int kt, int nt, char* s0, char* s1, char* s2) {
;     ...
;   __syncthreads();
; #pragma unroll
;   for (int i = 0; i < 16; ++i) {
;     int kl = (tid >> 6) + 4 * i, nl = tid & 63;
;     int k = kt * 64 + kl, n = nt * 64 + nl;
;     tile[kl * 65 + nl] = (n < N) ? src[(size_t)k * N + n] : 0.f;
;   }
;   __syncthreads();
; #pragma unroll
;   for (int i = 0; i < 16; ++i) {
;     int nl = (tid >> 6) + 4 * i, kl = tid & 63;
;     int k = kt * 64 + kl, n = nt * 64 + nl;
;     float v = tile[kl * 65 + nl];
;     float sc = scale ? scale[k] : 1.f;
;     dst[(size_t)n * K + k] = (u16)(pack2(v * sc, 0.f) & 0xffffu);
;     if (dst2) dst2[(size_t)n * K + k] = (u16)(pack2(v, 0.f) & 0xffffu);
;   }
; DI void wprep_job(const int tid_, const Params& p, int l, int j, char* s0, char* s1, char* s2) {
;     ...
;     transpose_job(tid_, p.in[I_W2] + (size_t)l * 64 * 512, nullptr, (u16*)(p.ws + WS_W2) + (size_t)l * 512 * 64, nullptr, 64, 512, 0, j - 1376, s0, s1, s2);
.LBB0_1079:
	s_andn2_b64 vcc, exec, s[2:3]
	s_cbranch_vccnz .LBB0_1081
	v_add_u32_e32 v0, s9, v74
	v_add_u32_e32 v0, 0x6600, v0
	v_lshl_add_u64 v[70:71], v[0:1], 2, s[14:15]
	v_lshl_add_u64 v[72:73], v[70:71], 0, v[34:35]
	s_waitcnt lgkmcnt(0)
	s_barrier
	flat_load_dword v206, v[72:73]
	v_add_u32_e32 v5, v75, v76
	v_lshl_add_u64 v[72:73], v[70:71], 0, v[36:37]
	flat_load_dword v207, v[72:73]
	v_lshl_add_u64 v[72:73], v[70:71], 0, v[38:39]
	flat_load_dword v208, v[72:73]
	v_lshl_add_u64 v[72:73], v[70:71], 0, v[40:41]
	flat_load_dword v209, v[72:73]
	v_lshl_add_u64 v[72:73], v[70:71], 0, v[42:43]
	flat_load_dword v210, v[72:73]
	v_lshl_add_u64 v[72:73], v[70:71], 0, v[44:45]
	flat_load_dword v211, v[72:73]
	v_lshl_add_u64 v[72:73], v[70:71], 0, v[46:47]
	s_waitcnt vmcnt(5) lgkmcnt(0)
	ds_write_b32 v5, v206
	s_waitcnt vmcnt(4)
	ds_write_b32 v5, v207 offset:1040
	s_waitcnt vmcnt(3)
	ds_write_b32 v5, v208 offset:2080
	s_waitcnt vmcnt(2)
	ds_write_b32 v5, v209 offset:3120
	s_waitcnt vmcnt(1)
	ds_write_b32 v5, v210 offset:4160
	s_waitcnt vmcnt(0)
	ds_write_b32 v5, v211 offset:5200
	flat_load_dword v206, v[72:73]
	v_add_u32_e32 v5, v75, v77
	v_lshl_add_u64 v[72:73], v[70:71], 0, v[48:49]
	flat_load_dword v207, v[72:73]
	v_lshl_add_u64 v[72:73], v[70:71], 0, v[50:51]
	flat_load_dword v208, v[72:73]
	v_lshl_add_u64 v[72:73], v[70:71], 0, v[52:53]
	flat_load_dword v209, v[72:73]
	v_lshl_add_u64 v[72:73], v[70:71], 0, v[54:55]
	flat_load_dword v210, v[72:73]
	v_lshl_add_u64 v[72:73], v[70:71], 0, v[56:57]
	flat_load_dword v211, v[72:73]
	v_lshl_add_u64 v[72:73], v[70:71], 0, v[58:59]
	flat_load_dword v212, v[72:73]
	v_lshl_add_u64 v[72:73], v[70:71], 0, v[60:61]
	flat_load_dword v213, v[72:73]
	v_lshl_add_u64 v[72:73], v[70:71], 0, v[62:63]
	v_lshl_add_u64 v[70:71], v[70:71], 0, v[64:65]
	flat_load_dword v214, v[72:73]
	flat_load_dword v215, v[70:71]
	s_waitcnt vmcnt(9) lgkmcnt(0)
	ds_write_b32 v5, v206
	s_waitcnt vmcnt(8)
	ds_write_b32 v5, v207 offset:1040
	s_waitcnt vmcnt(7)
	ds_write_b32 v5, v208 offset:2080
	s_waitcnt vmcnt(6)
	ds_write_b32 v5, v209 offset:3120
	s_waitcnt vmcnt(5)
	ds_write_b32 v5, v210 offset:4160
	s_waitcnt vmcnt(4)
	ds_write_b32 v5, v211 offset:5200
	s_waitcnt vmcnt(3)
	ds_write_b32 v5, v212 offset:6240
	s_waitcnt vmcnt(2)
	ds_write_b32 v5, v213 offset:7280
	s_waitcnt vmcnt(1)
	ds_write_b32 v5, v214 offset:8320
	s_waitcnt vmcnt(0)
	ds_write_b32 v5, v215 offset:9360
	s_waitcnt lgkmcnt(0)
	s_barrier
	v_add_u32_e32 v0, s9, v2
	ds_read2_b32 v[72:73], v78 offset1:4
	ds_read2_b32 v[80:81], v78 offset0:8 offset1:12
	v_add_u32_e32 v70, 0x6600, v0
	v_ashrrev_i32_e32 v71, 31, v70
	v_lshlrev_b64 v[70:71], 7, v[70:71]
	s_waitcnt lgkmcnt(1)
	v_cvt_pk_bf16_f32 v5, v72, s0
	v_lshl_add_u64 v[70:71], v[68:69], 0, v[70:71]
	flat_store_short v[70:71], v5
	v_add_u32_e32 v70, 0x6604, v0
	v_ashrrev_i32_e32 v71, 31, v70
	v_lshlrev_b64 v[70:71], 7, v[70:71]
	v_cvt_pk_bf16_f32 v5, v73, s0
	v_lshl_add_u64 v[70:71], v[68:69], 0, v[70:71]
	flat_store_short v[70:71], v5
	v_add_u32_e32 v70, 0x6608, v0
	v_ashrrev_i32_e32 v71, 31, v70
	v_lshlrev_b64 v[70:71], 7, v[70:71]
	s_waitcnt lgkmcnt(0)
	v_cvt_pk_bf16_f32 v5, v80, s0
	v_lshl_add_u64 v[70:71], v[68:69], 0, v[70:71]
	flat_store_short v[70:71], v5
	v_add_u32_e32 v70, 0x660c, v0
	v_ashrrev_i32_e32 v71, 31, v70
	v_lshlrev_b64 v[70:71], 7, v[70:71]
	ds_read2_b32 v[72:73], v78 offset0:16 offset1:20
	v_cvt_pk_bf16_f32 v5, v81, s0
	v_lshl_add_u64 v[70:71], v[68:69], 0, v[70:71]
	flat_store_short v[70:71], v5
	v_add_u32_e32 v70, 0x6610, v0
	v_ashrrev_i32_e32 v71, 31, v70
	v_lshlrev_b64 v[70:71], 7, v[70:71]
	s_waitcnt lgkmcnt(0)
	v_cvt_pk_bf16_f32 v5, v72, s0
	v_lshl_add_u64 v[70:71], v[68:69], 0, v[70:71]
	flat_store_short v[70:71], v5
	v_add_u32_e32 v70, 0x6614, v0
	v_ashrrev_i32_e32 v71, 31, v70
	v_cvt_pk_bf16_f32 v5, v73, s0
	v_lshlrev_b64 v[70:71], 7, v[70:71]
	ds_read2_b32 v[72:73], v78 offset0:24 offset1:28
	v_lshl_add_u64 v[70:71], v[68:69], 0, v[70:71]
	flat_store_short v[70:71], v5
	v_add_u32_e32 v70, 0x6618, v0
	v_ashrrev_i32_e32 v71, 31, v70
	v_lshlrev_b64 v[70:71], 7, v[70:71]
	s_waitcnt lgkmcnt(0)
	v_cvt_pk_bf16_f32 v5, v72, s0
	v_lshl_add_u64 v[70:71], v[68:69], 0, v[70:71]
	flat_store_short v[70:71], v5
	v_add_u32_e32 v70, 0x661c, v0
	v_ashrrev_i32_e32 v71, 31, v70
	v_cvt_pk_bf16_f32 v5, v73, s0
	v_lshlrev_b64 v[70:71], 7, v[70:71]
	ds_read2_b32 v[72:73], v78 offset0:32 offset1:36
	v_lshl_add_u64 v[70:71], v[68:69], 0, v[70:71]
	flat_store_short v[70:71], v5
	v_add_u32_e32 v70, 0x6620, v0
	v_ashrrev_i32_e32 v71, 31, v70
	v_lshlrev_b64 v[70:71], 7, v[70:71]
	s_waitcnt lgkmcnt(0)
	v_cvt_pk_bf16_f32 v5, v72, s0
	v_lshl_add_u64 v[70:71], v[68:69], 0, v[70:71]
	flat_store_short v[70:71], v5
	v_add_u32_e32 v70, 0x6624, v0
	v_ashrrev_i32_e32 v71, 31, v70
	v_lshlrev_b64 v[70:71], 7, v[70:71]
	ds_read2_b32 v[80:81], v78 offset0:40 offset1:44
	ds_read2_b32 v[82:83], v78 offset0:48 offset1:52
	v_cvt_pk_bf16_f32 v5, v73, s0
	v_lshl_add_u64 v[70:71], v[68:69], 0, v[70:71]
	flat_store_short v[70:71], v5
	v_add_u32_e32 v70, 0x6628, v0
	v_ashrrev_i32_e32 v71, 31, v70
	v_lshlrev_b64 v[70:71], 7, v[70:71]
	s_waitcnt lgkmcnt(0)
	v_cvt_pk_bf16_f32 v5, v80, s0
	v_lshl_add_u64 v[70:71], v[68:69], 0, v[70:71]
	flat_store_short v[70:71], v5
	v_add_u32_e32 v70, 0x662c, v0
	v_ashrrev_i32_e32 v71, 31, v70
	v_lshlrev_b64 v[70:71], 7, v[70:71]
	v_cvt_pk_bf16_f32 v5, v81, s0
	v_lshl_add_u64 v[70:71], v[68:69], 0, v[70:71]
	flat_store_short v[70:71], v5
	v_add_u32_e32 v70, 0x6630, v0
	v_ashrrev_i32_e32 v71, 31, v70
	v_lshlrev_b64 v[70:71], 7, v[70:71]
	v_cvt_pk_bf16_f32 v5, v82, s0
	v_lshl_add_u64 v[70:71], v[68:69], 0, v[70:71]
	flat_store_short v[70:71], v5
	v_add_u32_e32 v70, 0x6634, v0
	v_ashrrev_i32_e32 v71, 31, v70
	v_lshlrev_b64 v[70:71], 7, v[70:71]
	ds_read2_b32 v[72:73], v78 offset0:56 offset1:60
	v_cvt_pk_bf16_f32 v5, v83, s0
	v_lshl_add_u64 v[70:71], v[68:69], 0, v[70:71]
	flat_store_short v[70:71], v5
	v_add_u32_e32 v70, 0x6638, v0
	v_ashrrev_i32_e32 v71, 31, v70
	v_lshlrev_b64 v[70:71], 7, v[70:71]
	s_waitcnt lgkmcnt(0)
	v_cvt_pk_bf16_f32 v5, v72, s0
	v_lshl_add_u64 v[70:71], v[68:69], 0, v[70:71]
	flat_store_short v[70:71], v5
	v_add_u32_e32 v70, 0x663c, v0
	v_ashrrev_i32_e32 v71, 31, v70
	v_lshlrev_b64 v[70:71], 7, v[70:71]
	v_cvt_pk_bf16_f32 v0, v73, s0
	v_lshl_add_u64 v[70:71], v[68:69], 0, v[70:71]
	flat_store_short v[70:71], v0
